# speedup vs baseline: 1.1027x; 1.0134x over previous
; DEV int otid() { int t = threadIdx.x; asm volatile("" : "+v"(t)); return t; }
;   const int tid = otid(), lane = tid & 63, w = __builtin_amdgcn_readfirstlane(tid >> 6), wm = w >> 1, wn = w & 1, r32 = lane & 31, hh = lane >> 5;
;   f32x16 acc[MI / 2][2][2];
; #pragma unroll
;   for (int h = 0; h < MI / 2; ++h) { acc[h][0][0] = zero16(); acc[h][0][1] = zero16(); acc[h][1][0] = zero16(); acc[h][1][1] = zero16(); }
;   const int lrow = lane >> 2, lp = (lane & 3) ^ ((lane >> 4) & 3);
;   const bf16_t* ag = uni_ptr(A + (size_t)m0 * lda + kbeg);
;   const bf16_t* bg = uni_ptr(Bt + (size_t)n0 * ldb + kbeg);
;   const unsigned voffa = ((unsigned)lrow * (unsigned)lda + (unsigned)lp * 8u) * 2u;
;   const unsigned voffb = ((unsigned)lrow * (unsigned)ldb + (unsigned)lp * 8u) * 2u;
;   const int nk = (kend - kbeg) >> 5;
;   if (!pre) {
;     asm volatile("s_waitcnt vmcnt(0)" ::: "memory");
;     g2_issue<MI>(ag, bg, lda, ldb, voffa, voffb, lds, w);
;     if (nk > 1) g2_issue<MI>(ag + 32, bg + 32, lda, ldb, voffa, voffb, lds + G2_STAGE, w);
;   }
;   const int key = (r32 >> 2) & 3;
;   const int aoff = (wm * (MI * 32) + r32) * 64;
;   const int boff = 16384 + (wn * 64 + r32) * 64;
;   const int p0 = ((0 + hh) ^ key) * 16, p1 = ((2 + hh) ^ key) * 16;
;   const unsigned lbase = (unsigned)(size_t)lds;
;   const unsigned la0 = lbase + aoff + p0, la1 = lbase + aoff + p1, lb0 = lbase + boff + p0, lb1 = lbase + boff + p1;
;   int stg = 0;
;   for (int kt = 0; kt < nk; ++kt) {
;     if (kt + 1 < nk) { if (MI == 4) asm volatile("s_waitcnt vmcnt(6)" ::: "memory"); else asm volatile("s_waitcnt vmcnt(4)" ::: "memory"); } else asm volatile("s_waitcnt vmcnt(0)" ::: "memory");
;     __builtin_amdgcn_s_barrier();
.LBB0_78:
	s_xor_b64 s[0:1], s[2:3], -1
	s_and_b32 s52, s53, 0xffffff80
	s_and_b32 s53, s53, 64
	s_lshl_b32 s59, s54, 12
	s_lshl_b32 s58, s55, 10
	s_lshl_b32 s57, s56, 10
	s_lshl_b32 s56, s63, 10
	s_lshl_b32 s55, s54, 11
	s_lshl_b32 s54, s64, 10
	s_add_u32 s16, s60, 0x80
	s_addc_u32 s17, s61, 0
	s_lshl_b64 s[4:5], s[4:5], 1
	s_add_u32 s60, s16, s4
	s_addc_u32 s61, s17, s5
	s_lshl_b64 s[8:9], s[8:9], 1
	s_add_u32 s63, s16, s8
	s_addc_u32 s64, s17, s9
	s_add_u32 s18, s18, 0x80
	s_addc_u32 s19, s19, 0
	s_lshl_b64 s[10:11], s[10:11], 1
	s_add_u32 s74, s18, s10
	s_addc_u32 s75, s19, s11
	s_lshl_b64 s[12:13], s[12:13], 1
	s_add_u32 s76, s18, s12
	v_and_b32_e32 v3, 63, v2
	s_addc_u32 s77, s19, s13
	s_lshl_b64 s[14:15], s[14:15], 1
	v_and_b32_e32 v130, 31, v2
	v_lshrrev_b32_e32 v133, 5, v3
	v_lshrrev_b32_e32 v3, 2, v2
	v_bfe_u32 v2, v2, 2, 2
	s_add_u32 s78, s18, s14
	v_or_b32_e32 v4, s52, v130
	v_bitop3_b32 v2, v133, v2, 2 bitop3:0x36
	s_addc_u32 s79, s19, s15
	s_lshl_b64 s[16:17], s[6:7], 1
	v_lshlrev_b32_e32 v141, 6, v4
	v_or_b32_e32 v4, s53, v130
	v_bitop3_b32 v3, v133, v3, 3 bitop3:0x78
	v_lshlrev_b32_e32 v138, 4, v2
	s_add_u32 s7, s18, s16
	v_mov_b32_e32 v2, 0
	v_lshl_or_b32 v143, v4, 6, v209
	v_lshlrev_b32_e32 v145, 4, v3
	s_addc_u32 s80, s19, s17
	s_mov_b32 s6, 0
	s_mov_b64 s[18:19], 0
	v_mov_b32_e32 v3, v2
	v_mov_b32_e32 v4, v2
	v_mov_b32_e32 v5, v2
	v_mov_b32_e32 v6, v2
	v_mov_b32_e32 v7, v2
	v_mov_b32_e32 v8, v2
	v_mov_b32_e32 v9, v2
	v_mov_b32_e32 v10, v2
	v_mov_b32_e32 v11, v2
	v_mov_b32_e32 v12, v2
	v_mov_b32_e32 v13, v2
	v_mov_b32_e32 v14, v2
	v_mov_b32_e32 v15, v2
	v_mov_b32_e32 v16, v2
	v_mov_b32_e32 v17, v2
	v_mov_b32_e32 v18, v2
	v_mov_b32_e32 v19, v2
	v_mov_b32_e32 v20, v2
	v_mov_b32_e32 v21, v2
	v_mov_b32_e32 v22, v2
	v_mov_b32_e32 v23, v2
	v_mov_b32_e32 v24, v2
	v_mov_b32_e32 v25, v2
	v_mov_b32_e32 v26, v2
	v_mov_b32_e32 v27, v2
	v_mov_b32_e32 v28, v2
	v_mov_b32_e32 v29, v2
	v_mov_b32_e32 v30, v2
	v_mov_b32_e32 v31, v2
	v_mov_b32_e32 v32, v2
	v_mov_b32_e32 v33, v2
	v_mov_b32_e32 v34, v2
	v_mov_b32_e32 v35, v2
	v_mov_b32_e32 v36, v2
	v_mov_b32_e32 v37, v2
	v_mov_b32_e32 v38, v2
	v_mov_b32_e32 v39, v2
	v_mov_b32_e32 v40, v2
	v_mov_b32_e32 v41, v2
	v_mov_b32_e32 v42, v2
	v_mov_b32_e32 v43, v2
	v_mov_b32_e32 v44, v2
	v_mov_b32_e32 v45, v2
	v_mov_b32_e32 v46, v2
	v_mov_b32_e32 v47, v2
	v_mov_b32_e32 v48, v2
	v_mov_b32_e32 v49, v2
	v_mov_b32_e32 v50, v2
	v_mov_b32_e32 v51, v2
	v_mov_b32_e32 v52, v2
	v_mov_b32_e32 v53, v2
	v_mov_b32_e32 v54, v2
	v_mov_b32_e32 v55, v2
	v_mov_b32_e32 v56, v2
	v_mov_b32_e32 v57, v2
	v_mov_b32_e32 v58, v2
	v_mov_b32_e32 v59, v2
	v_mov_b32_e32 v60, v2
	v_mov_b32_e32 v61, v2
	v_mov_b32_e32 v62, v2
	v_mov_b32_e32 v63, v2
	v_mov_b32_e32 v64, v2
	v_mov_b32_e32 v65, v2
	v_mov_b32_e32 v66, v2
	v_mov_b32_e32 v67, v2
	v_mov_b32_e32 v68, v2
	v_mov_b32_e32 v69, v2
	v_mov_b32_e32 v70, v2
	v_mov_b32_e32 v71, v2
	v_mov_b32_e32 v72, v2
	v_mov_b32_e32 v73, v2
	v_mov_b32_e32 v74, v2
	v_mov_b32_e32 v75, v2
	v_mov_b32_e32 v76, v2
	v_mov_b32_e32 v77, v2
	v_mov_b32_e32 v78, v2
	v_mov_b32_e32 v79, v2
	v_mov_b32_e32 v80, v2
	v_mov_b32_e32 v81, v2
	v_mov_b32_e32 v82, v2
	v_mov_b32_e32 v83, v2
	v_mov_b32_e32 v84, v2
	v_mov_b32_e32 v85, v2
	v_mov_b32_e32 v86, v2
	v_mov_b32_e32 v87, v2
	v_mov_b32_e32 v88, v2
	v_mov_b32_e32 v89, v2
	v_mov_b32_e32 v90, v2
	v_mov_b32_e32 v91, v2
	v_mov_b32_e32 v92, v2
	v_mov_b32_e32 v93, v2
	v_mov_b32_e32 v94, v2
	v_mov_b32_e32 v95, v2
	v_mov_b32_e32 v96, v2
	v_mov_b32_e32 v97, v2
	v_mov_b32_e32 v98, v2
	v_mov_b32_e32 v99, v2
	v_mov_b32_e32 v100, v2
	v_mov_b32_e32 v101, v2
	v_mov_b32_e32 v102, v2
	v_mov_b32_e32 v103, v2
	v_mov_b32_e32 v104, v2
	v_mov_b32_e32 v105, v2
	v_mov_b32_e32 v106, v2
	v_mov_b32_e32 v107, v2
	v_mov_b32_e32 v108, v2
	v_mov_b32_e32 v109, v2
	v_mov_b32_e32 v110, v2
	v_mov_b32_e32 v111, v2
	v_mov_b32_e32 v112, v2
	v_mov_b32_e32 v113, v2
	v_mov_b32_e32 v114, v2
	v_mov_b32_e32 v115, v2
	v_mov_b32_e32 v116, v2
	v_mov_b32_e32 v117, v2
	v_mov_b32_e32 v118, v2
	v_mov_b32_e32 v119, v2
	v_mov_b32_e32 v120, v2
	v_mov_b32_e32 v121, v2
	v_mov_b32_e32 v122, v2
	v_mov_b32_e32 v123, v2
	v_mov_b32_e32 v124, v2
	v_mov_b32_e32 v125, v2
	v_mov_b32_e32 v126, v2
	v_mov_b32_e32 v127, v2
	v_mov_b32_e32 v128, v2
	v_mov_b32_e32 v129, v2
	v_lshlrev_b32_e32 v254, 4, v200
.LBB0_79:
	s_cmp_gt_i32 s6, 0
	s_cselect_b32 s81, -1, 2
	s_add_i32 s81, s81, s6
	s_mulk_i32 s81, 0x6000
	s_add_u32 s82, s7, s18
	s_addc_u32 s83, s80, s19
	s_add_i32 s84, s59, s81
	s_cmp_eq_u32 s18, 0
	s_cbranch_scc1 .Lhy4_first_down
	s_waitcnt vmcnt(0)
	s_barrier
	s_add_i32 s98, s6, 1
	s_cmp_lg_u32 s6, 2
	s_cselect_b32 s98, s98, 0
	s_mul_i32 s98, s98, 0x6000
	s_add_i32 s99, s59, s98
	v_add_u32_e32 v238, s99, v254
	ds_write_b128 v238, v[214:217]
	s_add_i32 s99, s58, s98
	v_add_u32_e32 v255, s99, v254
	ds_write_b128 v255, v[218:221]
	s_add_i32 s99, s57, s98
	v_add_u32_e32 v238, s99, v254
	ds_write_b128 v238, v[222:225]
	s_add_i32 s99, s56, s98
	v_add_u32_e32 v255, s99, v254
	ds_write_b128 v255, v[226:229]
	s_add_i32 s99, s55, s98
	s_addk_i32 s99, 0x4000
	v_add_u32_e32 v238, s99, v254
	ds_write_b128 v238, v[230:233]
	s_add_i32 s99, s54, s98
	s_addk_i32 s99, 0x4000
	v_add_u32_e32 v255, s99, v254
	ds_write_b128 v255, v[234:237]
	s_branch .Lhy4_issue_down

; DEV f32x16 mfma(bf16x8 a, bf16x8 b, f32x16 c) { return __builtin_amdgcn_mfma_f32_32x32x16_bf16(a, b, c, 0, 0, 0); }
;     ...
;   for (int kt = 0; kt < nk; ++kt) {
;     if (kt + 1 < nk) { if (MI == 4) asm volatile("s_waitcnt vmcnt(6)" ::: "memory"); else asm volatile("s_waitcnt vmcnt(4)" ::: "memory"); } else asm volatile("s_waitcnt vmcnt(0)" ::: "memory");
;     __builtin_amdgcn_s_barrier();
;     if (kt + 2 < nk) { int s2 = stg + 2; if (s2 >= 3) s2 -= 3; g2_issue<MI>(ag + (size_t)(kt + 2) * 32, bg + (size_t)(kt + 2) * 32, lda, ldb, voffa, voffb, lds + s2 * G2_STAGE, w); }
;     const unsigned so = (unsigned)(stg * G2_STAGE);
;     __builtin_amdgcn_s_setprio(1);
; #pragma unroll
;     for (int ks = 0; ks < 2; ++ks) {
;       const unsigned aa = (ks ? la1 : la0) + so, bb = (ks ? lb1 : lb0) + so;
;       bf16x8 fb0, fb1, fa0, fa1, fa2, fa3;
;       asm volatile("ds_read_b128 %0, %1" : "=v"(fb0) : "v"(bb));
;       asm volatile("ds_read_b128 %0, %1 offset:2048" : "=v"(fb1) : "v"(bb));
;       asm volatile("ds_read_b128 %0, %1" : "=v"(fa0) : "v"(aa));
;       asm volatile("ds_read_b128 %0, %1 offset:2048" : "=v"(fa1) : "v"(aa));
;       if constexpr (MI == 4) {
;         asm volatile("ds_read_b128 %0, %1 offset:4096" : "=v"(fa2) : "v"(aa));
;         asm volatile("ds_read_b128 %0, %1 offset:6144" : "=v"(fa3) : "v"(aa));
;         __builtin_amdgcn_sched_barrier(0);
;         asm volatile("s_waitcnt lgkmcnt(3)" : "+v"(fb0), "+v"(fb1), "+v"(fa0));
;         acc[0][0][0] = mfma(fa0, fb0, acc[0][0][0]); acc[0][0][1] = mfma(fa0, fb1, acc[0][0][1]); __builtin_amdgcn_sched_barrier(0);
;         asm volatile("s_waitcnt lgkmcnt(2)" : "+v"(fa1));
;         acc[0][1][0] = mfma(fa1, fb0, acc[0][1][0]); acc[0][1][1] = mfma(fa1, fb1, acc[0][1][1]); __builtin_amdgcn_sched_barrier(0);
;         asm volatile("s_waitcnt lgkmcnt(1)" : "+v"(fa2));
;         acc[MI / 2 - 1][0][0] = mfma(fa2, fb0, acc[MI / 2 - 1][0][0]); acc[MI / 2 - 1][0][1] = mfma(fa2, fb1, acc[MI / 2 - 1][0][1]); __builtin_amdgcn_sched_barrier(0);
;         asm volatile("s_waitcnt lgkmcnt(0)" : "+v"(fa3));
;         acc[MI / 2 - 1][1][0] = mfma(fa3, fb0, acc[MI / 2 - 1][1][0]); acc[MI / 2 - 1][1][1] = mfma(fa3, fb1, acc[MI / 2 - 1][1][1]); __builtin_amdgcn_sched_barrier(0);
;       } else {
;         __builtin_amdgcn_sched_barrier(0);
;         asm volatile("s_waitcnt lgkmcnt(1)" : "+v"(fb0), "+v"(fb1), "+v"(fa0));
.Lhy4_issue_down:
	s_mul_i32 s99, s6, 0x6000
	s_setprio 1
	v_add_u32_e32 v147, s99, v141
	v_add_u32_e32 v149, s99, v143
	v_add_u32_e32 v172, v147, v145
	v_add_u32_e32 v156, v149, v145
	ds_read_b128 v[152:155], v156
	ds_read_b128 v[156:159], v156 offset:2048
	ds_read_b128 v[160:163], v172
	ds_read_b128 v[164:167], v172 offset:2048
	ds_read_b128 v[168:171], v172 offset:4096
	ds_read_b128 v[172:175], v172 offset:6144
	v_add_u32_e32 v147, v147, v138
	v_add_u32_e32 v149, v149, v138
	ds_read_b128 v[180:183], v149
	ds_read_b128 v[184:187], v149 offset:2048
	ds_read_b128 v[188:191], v147
	ds_read_b128 v[242:245], v147 offset:2048
	ds_read_b128 v[246:249], v147 offset:4096
	ds_read_b128 v[250:253], v147 offset:6144
	s_cmpk_eq_i32 s18, 0x2b80
	s_cbranch_scc1 .Lhy4_noissueE_down
	s_nop 0
	s_waitcnt lgkmcnt(9)
	s_nop 0
	v_mfma_f32_32x32x16_bf16 v[114:129], v[160:163], v[152:155], v[114:129]
	v_mfma_f32_32x32x16_bf16 v[98:113], v[160:163], v[156:159], v[98:113]
	s_mov_b32 m0, s84
	s_nop 0
	global_load_lds_dwordx4 v1, s[82:83]
	global_load_dwordx4 v[214:217], v1, s[82:83] offset:64
	s_waitcnt lgkmcnt(8)
	s_nop 0
	v_mfma_f32_32x32x16_bf16 v[82:97], v[164:167], v[152:155], v[82:97]
	v_mfma_f32_32x32x16_bf16 v[66:81], v[164:167], v[156:159], v[66:81]
	s_add_u32 s82, s78, s18
	s_addc_u32 s83, s79, s19
	s_add_i32 s84, s58, s81
	s_mov_b32 m0, s84
	s_nop 0
	global_load_lds_dwordx4 v1, s[82:83]
	global_load_dwordx4 v[218:221], v1, s[82:83] offset:64
	s_waitcnt lgkmcnt(7)
	s_nop 0
	v_mfma_f32_32x32x16_bf16 v[50:65], v[168:171], v[152:155], v[50:65]
	v_mfma_f32_32x32x16_bf16 v[34:49], v[168:171], v[156:159], v[34:49]
	s_add_u32 s82, s76, s18
	s_addc_u32 s83, s77, s19
	s_add_i32 s84, s57, s81
	s_mov_b32 m0, s84
	s_nop 0
	global_load_lds_dwordx4 v1, s[82:83]
	global_load_dwordx4 v[222:225], v1, s[82:83] offset:64
	s_waitcnt lgkmcnt(6)
	s_nop 0
	v_mfma_f32_32x32x16_bf16 v[18:33], v[172:175], v[152:155], v[18:33]
	v_mfma_f32_32x32x16_bf16 v[2:17], v[172:175], v[156:159], v[2:17]
	s_branch .Lhy4_afterE_down
.Lhy4_noissueE_down:
	s_nop 0
	s_waitcnt lgkmcnt(9)
	s_nop 0
	v_mfma_f32_32x32x16_bf16 v[114:129], v[160:163], v[152:155], v[114:129]
	v_mfma_f32_32x32x16_bf16 v[98:113], v[160:163], v[156:159], v[98:113]
	s_waitcnt lgkmcnt(8)
	s_nop 0
	v_mfma_f32_32x32x16_bf16 v[82:97], v[164:167], v[152:155], v[82:97]
	v_mfma_f32_32x32x16_bf16 v[66:81], v[164:167], v[156:159], v[66:81]
	s_waitcnt lgkmcnt(7)
	s_nop 0
	v_mfma_f32_32x32x16_bf16 v[50:65], v[168:171], v[152:155], v[50:65]
	v_mfma_f32_32x32x16_bf16 v[34:49], v[168:171], v[156:159], v[34:49]
	s_waitcnt lgkmcnt(6)
	s_nop 0
	v_mfma_f32_32x32x16_bf16 v[18:33], v[172:175], v[152:155], v[18:33]
	v_mfma_f32_32x32x16_bf16 v[2:17], v[172:175], v[156:159], v[2:17]
.Lhy4_afterE_down:
	s_nop 0
	s_waitcnt lgkmcnt(3)
	s_nop 0
	v_mfma_f32_32x32x16_bf16 v[114:129], v[188:191], v[180:183], v[114:129]
	v_mfma_f32_32x32x16_bf16 v[98:113], v[188:191], v[184:187], v[98:113]
	s_waitcnt lgkmcnt(2)
	s_nop 0
	v_mfma_f32_32x32x16_bf16 v[82:97], v[242:245], v[180:183], v[82:97]
	v_mfma_f32_32x32x16_bf16 v[66:81], v[242:245], v[184:187], v[66:81]
	s_waitcnt lgkmcnt(1)
	s_nop 0
	v_mfma_f32_32x32x16_bf16 v[50:65], v[246:249], v[180:183], v[50:65]
	v_mfma_f32_32x32x16_bf16 v[34:49], v[246:249], v[184:187], v[34:49]
	s_waitcnt lgkmcnt(0)
	s_nop 0
	v_mfma_f32_32x32x16_bf16 v[18:33], v[250:253], v[180:183], v[18:33]
	v_mfma_f32_32x32x16_bf16 v[2:17], v[250:253], v[184:187], v[2:17]
	s_setprio 0
	s_add_i32 s98, s6, 1
	s_cmp_lg_u32 s6, 2
	s_cselect_b32 s6, s98, 0
	s_waitcnt vmcnt(6)
	s_barrier
	s_mul_i32 s99, s6, 0x6000
	s_setprio 1
	v_add_u32_e32 v147, s99, v141
	v_add_u32_e32 v149, s99, v143
	v_add_u32_e32 v172, v147, v145
	v_add_u32_e32 v156, v149, v145
	ds_read_b128 v[152:155], v156
	ds_read_b128 v[156:159], v156 offset:2048
	ds_read_b128 v[160:163], v172
	ds_read_b128 v[164:167], v172 offset:2048
	ds_read_b128 v[168:171], v172 offset:4096
	ds_read_b128 v[172:175], v172 offset:6144
	v_add_u32_e32 v147, v147, v138
	v_add_u32_e32 v149, v149, v138
	ds_read_b128 v[180:183], v149
	ds_read_b128 v[184:187], v149 offset:2048
	ds_read_b128 v[188:191], v147
	ds_read_b128 v[242:245], v147 offset:2048
	ds_read_b128 v[246:249], v147 offset:4096
	ds_read_b128 v[250:253], v147 offset:6144
	s_cmpk_eq_i32 s18, 0x2b80
	s_cbranch_scc1 .Lhy4_noissueO_down
	s_nop 0
	s_waitcnt lgkmcnt(9)
	s_nop 0
	v_mfma_f32_32x32x16_bf16 v[114:129], v[160:163], v[152:155], v[114:129]
	v_mfma_f32_32x32x16_bf16 v[98:113], v[160:163], v[156:159], v[98:113]
	s_add_u32 s82, s74, s18
	s_addc_u32 s83, s75, s19
	s_add_i32 s84, s56, s81
	s_addk_i32 s81, 0x4000
	s_mov_b32 m0, s84
	s_nop 0
	global_load_lds_dwordx4 v1, s[82:83]
	global_load_dwordx4 v[226:229], v1, s[82:83] offset:64
	s_waitcnt lgkmcnt(8)
	s_nop 0
	v_mfma_f32_32x32x16_bf16 v[82:97], v[164:167], v[152:155], v[82:97]
	v_mfma_f32_32x32x16_bf16 v[66:81], v[164:167], v[156:159], v[66:81]
	s_add_u32 s82, s63, s18
	s_addc_u32 s83, s64, s19
	s_add_i32 s84, s81, s55
	s_mov_b32 m0, s84
	s_nop 0
	global_load_lds_dwordx4 v1, s[82:83]
	global_load_dwordx4 v[230:233], v1, s[82:83] offset:64
	s_waitcnt lgkmcnt(7)
	s_nop 0
	v_mfma_f32_32x32x16_bf16 v[50:65], v[168:171], v[152:155], v[50:65]
	v_mfma_f32_32x32x16_bf16 v[34:49], v[168:171], v[156:159], v[34:49]
	s_add_u32 s82, s60, s18
	s_addc_u32 s83, s61, s19
	s_add_i32 s81, s81, s54
	s_mov_b32 m0, s81
	s_nop 0
	global_load_lds_dwordx4 v1, s[82:83]
	global_load_dwordx4 v[234:237], v1, s[82:83] offset:64
	s_waitcnt lgkmcnt(6)
	s_nop 0
	v_mfma_f32_32x32x16_bf16 v[18:33], v[172:175], v[152:155], v[18:33]
	v_mfma_f32_32x32x16_bf16 v[2:17], v[172:175], v[156:159], v[2:17]
	s_branch .Lhy4_afterO_down

; DEV f32x16 mfma(bf16x8 a, bf16x8 b, f32x16 c) { return __builtin_amdgcn_mfma_f32_32x32x16_bf16(a, b, c, 0, 0, 0); }
;     ...
;   for (int kt = 0; kt < nk; ++kt) {
;     if (kt + 1 < nk) { if (MI == 4) asm volatile("s_waitcnt vmcnt(6)" ::: "memory"); else asm volatile("s_waitcnt vmcnt(4)" ::: "memory"); } else asm volatile("s_waitcnt vmcnt(0)" ::: "memory");
;     __builtin_amdgcn_s_barrier();
;     if (kt + 2 < nk) { int s2 = stg + 2; if (s2 >= 3) s2 -= 3; g2_issue<MI>(ag + (size_t)(kt + 2) * 32, bg + (size_t)(kt + 2) * 32, lda, ldb, voffa, voffb, lds + s2 * G2_STAGE, w); }
;     const unsigned so = (unsigned)(stg * G2_STAGE);
;     __builtin_amdgcn_s_setprio(1);
; #pragma unroll
;     for (int ks = 0; ks < 2; ++ks) {
;       const unsigned aa = (ks ? la1 : la0) + so, bb = (ks ? lb1 : lb0) + so;
;       bf16x8 fb0, fb1, fa0, fa1, fa2, fa3;
;       asm volatile("ds_read_b128 %0, %1" : "=v"(fb0) : "v"(bb));
;       asm volatile("ds_read_b128 %0, %1 offset:2048" : "=v"(fb1) : "v"(bb));
;       asm volatile("ds_read_b128 %0, %1" : "=v"(fa0) : "v"(aa));
;       asm volatile("ds_read_b128 %0, %1 offset:2048" : "=v"(fa1) : "v"(aa));
;       if constexpr (MI == 4) {
;         asm volatile("ds_read_b128 %0, %1 offset:4096" : "=v"(fa2) : "v"(aa));
;         asm volatile("ds_read_b128 %0, %1 offset:6144" : "=v"(fa3) : "v"(aa));
;         __builtin_amdgcn_sched_barrier(0);
;         asm volatile("s_waitcnt lgkmcnt(3)" : "+v"(fb0), "+v"(fb1), "+v"(fa0));
;         acc[0][0][0] = mfma(fa0, fb0, acc[0][0][0]); acc[0][0][1] = mfma(fa0, fb1, acc[0][0][1]); __builtin_amdgcn_sched_barrier(0);
;         asm volatile("s_waitcnt lgkmcnt(2)" : "+v"(fa1));
;         acc[0][1][0] = mfma(fa1, fb0, acc[0][1][0]); acc[0][1][1] = mfma(fa1, fb1, acc[0][1][1]); __builtin_amdgcn_sched_barrier(0);
;         asm volatile("s_waitcnt lgkmcnt(1)" : "+v"(fa2));
;         acc[MI / 2 - 1][0][0] = mfma(fa2, fb0, acc[MI / 2 - 1][0][0]); acc[MI / 2 - 1][0][1] = mfma(fa2, fb1, acc[MI / 2 - 1][0][1]); __builtin_amdgcn_sched_barrier(0);
;         asm volatile("s_waitcnt lgkmcnt(0)" : "+v"(fa3));
;         acc[MI / 2 - 1][1][0] = mfma(fa3, fb0, acc[MI / 2 - 1][1][0]); acc[MI / 2 - 1][1][1] = mfma(fa3, fb1, acc[MI / 2 - 1][1][1]); __builtin_amdgcn_sched_barrier(0);
;       } else {
;         __builtin_amdgcn_sched_barrier(0);
;         asm volatile("s_waitcnt lgkmcnt(1)" : "+v"(fb0), "+v"(fb1), "+v"(fa0));
.Lhy4_afterO_down:
	s_nop 0
	s_waitcnt lgkmcnt(3)
	s_nop 0
	v_mfma_f32_32x32x16_bf16 v[114:129], v[188:191], v[180:183], v[114:129]
	v_mfma_f32_32x32x16_bf16 v[98:113], v[188:191], v[184:187], v[98:113]
	s_waitcnt lgkmcnt(2)
	s_nop 0
	v_mfma_f32_32x32x16_bf16 v[82:97], v[242:245], v[180:183], v[82:97]
	v_mfma_f32_32x32x16_bf16 v[66:81], v[242:245], v[184:187], v[66:81]
	s_waitcnt lgkmcnt(1)
	s_nop 0
	v_mfma_f32_32x32x16_bf16 v[50:65], v[246:249], v[180:183], v[50:65]
	v_mfma_f32_32x32x16_bf16 v[34:49], v[246:249], v[184:187], v[34:49]
	s_waitcnt lgkmcnt(0)
	s_nop 0
	v_mfma_f32_32x32x16_bf16 v[18:33], v[250:253], v[180:183], v[18:33]
	v_mfma_f32_32x32x16_bf16 v[2:17], v[250:253], v[184:187], v[2:17]
	s_add_i32 s98, s6, 1
	s_cmp_lg_u32 s6, 2
	s_cselect_b32 s6, s98, 0
	s_add_u32 s18, s18, 0x80
	s_addc_u32 s19, s19, 0
	s_cmpk_eq_i32 s18, 0x2c00
	s_cbranch_scc0 .LBB0_79
	s_setprio 0
	s_and_b64 vcc, exec, s[2:3]
	s_waitcnt lgkmcnt(0)
	s_barrier
	s_cbranch_vccz .LBB0_67
	s_lshl_b32 s2, s21, 8
	s_lshl_b32 s3, s22, 7
	s_mul_i32 s6, s21, 0x2c0000
	s_mul_hi_i32 s2, s2, 0x2c00
	s_add_u32 s18, s23, s6
	s_addc_u32 s19, s24, s2
	s_mul_i32 s2, s22, 0x160000
	s_mul_hi_i32 s3, s3, 0x2c00
	s_add_u32 s60, s25, s2
	s_addc_u32 s61, s26, s3
	s_add_u32 s2, s18, s16
	s_addc_u32 s3, s19, s17
	s_add_u32 s6, s18, s14
	s_addc_u32 s7, s19, s15
	s_add_u32 s12, s18, s12
	s_addc_u32 s13, s19, s13
	s_add_u32 s10, s18, s10
	s_mov_b32 m0, s59
	s_nop 0
	global_load_lds_dwordx4 v1, s[2:3]
	s_addc_u32 s11, s19, s11
	s_mov_b32 m0, s58
	s_nop 0
	global_load_lds_dwordx4 v1, s[6:7]
	s_add_u32 s8, s60, s8
	s_mov_b32 m0, s57
	s_nop 0
	global_load_lds_dwordx4 v1, s[12:13]
	s_addc_u32 s9, s61, s9
	s_add_i32 s14, s55, 0x4000
	s_mov_b32 m0, s56
	s_nop 0
	global_load_lds_dwordx4 v1, s[10:11]
	s_add_u32 s4, s60, s4
	s_mov_b32 m0, s14
	s_nop 0
	global_load_lds_dwordx4 v1, s[8:9]
	s_addc_u32 s5, s61, s5
	s_add_i32 s14, s54, 0x4000
	s_add_u32 s2, s2, 64
	s_mov_b32 m0, s14
	s_nop 0
	global_load_lds_dwordx4 v1, s[4:5]
	s_addc_u32 s3, s3, 0
	s_add_i32 s14, s59, 0x6000
	s_mov_b32 m0, s14
	s_nop 0
	global_load_lds_dwordx4 v1, s[2:3]
	s_add_u32 s2, s6, 64
	s_addc_u32 s3, s7, 0
	s_add_i32 s6, s58, 0x6000
	s_mov_b32 m0, s6
	s_nop 0
	global_load_lds_dwordx4 v1, s[2:3]
	s_add_u32 s2, s12, 64
	s_addc_u32 s3, s13, 0
	s_add_i32 s6, s57, 0x6000
	s_mov_b32 m0, s6
	s_nop 0
	global_load_lds_dwordx4 v1, s[2:3]
	s_add_u32 s2, s10, 64
	s_addc_u32 s3, s11, 0
	s_add_i32 s6, s56, 0x6000
	s_mov_b32 m0, s6
	s_nop 0
	global_load_lds_dwordx4 v1, s[2:3]
	s_add_u32 s2, s8, 64
	s_addc_u32 s3, s9, 0
	s_add_i32 s55, s55, 0xa000
	s_mov_b32 m0, s55
	s_nop 0
	global_load_lds_dwordx4 v1, s[2:3]
	s_add_u32 s2, s4, 64
	s_addc_u32 s3, s5, 0
	s_add_i32 s54, s54, 0xa000
	s_mov_b32 m0, s54
	s_nop 0
	global_load_lds_dwordx4 v1, s[2:3]
	s_branch .LBB0_67

; DEV int otid() { int t = threadIdx.x; asm volatile("" : "+v"(t)); return t; }
;   const int tid = otid(), lane = tid & 63, w = __builtin_amdgcn_readfirstlane(tid >> 6), wm = w >> 1, wn = w & 1, r32 = lane & 31, hh = lane >> 5;
;   f32x16 acc[MI / 2][2][2];
; #pragma unroll
;   for (int h = 0; h < MI / 2; ++h) { acc[h][0][0] = zero16(); acc[h][0][1] = zero16(); acc[h][1][0] = zero16(); acc[h][1][1] = zero16(); }
;   const int lrow = lane >> 2, lp = (lane & 3) ^ ((lane >> 4) & 3);
;   const bf16_t* ag = uni_ptr(A + (size_t)m0 * lda + kbeg);
;   const bf16_t* bg = uni_ptr(Bt + (size_t)n0 * ldb + kbeg);
;   const unsigned voffa = ((unsigned)lrow * (unsigned)lda + (unsigned)lp * 8u) * 2u;
;   const unsigned voffb = ((unsigned)lrow * (unsigned)ldb + (unsigned)lp * 8u) * 2u;
;   const int nk = (kend - kbeg) >> 5;
;   if (!pre) {
;     asm volatile("s_waitcnt vmcnt(0)" ::: "memory");
;     g2_issue<MI>(ag, bg, lda, ldb, voffa, voffb, lds, w);
;     if (nk > 1) g2_issue<MI>(ag + 32, bg + 32, lda, ldb, voffa, voffb, lds + G2_STAGE, w);
;   }
;   const int key = (r32 >> 2) & 3;
;   const int aoff = (wm * (MI * 32) + r32) * 64;
;   const int boff = 16384 + (wn * 64 + r32) * 64;
;   const int p0 = ((0 + hh) ^ key) * 16, p1 = ((2 + hh) ^ key) * 16;
;   const unsigned lbase = (unsigned)(size_t)lds;
;   const unsigned la0 = lbase + aoff + p0, la1 = lbase + aoff + p1, lb0 = lbase + boff + p0, lb1 = lbase + boff + p1;
;   int stg = 0;
;   for (int kt = 0; kt < nk; ++kt) {
;     if (kt + 1 < nk) { if (MI == 4) asm volatile("s_waitcnt vmcnt(6)" ::: "memory"); else asm volatile("s_waitcnt vmcnt(4)" ::: "memory"); } else asm volatile("s_waitcnt vmcnt(0)" ::: "memory");
;     __builtin_amdgcn_s_barrier();
;     if (kt + 2 < nk) { int s2 = stg + 2; if (s2 >= 3) s2 -= 3; g2_issue<MI>(ag + (size_t)(kt + 2) * 32, bg + (size_t)(kt + 2) * 32, lda, ldb, voffa, voffb, lds + s2 * G2_STAGE, w); }
.LBB0_117:
	s_and_b32 s3, s55, 0xffffff80
	s_and_b32 s5, s55, 64
	s_lshl_b32 s59, s54, 12
	s_lshl_b32 s58, s56, 10
	s_lshl_b32 s57, s57, 10
	s_lshl_b32 s56, s63, 10
	s_lshl_b32 s55, s54, 11
	s_lshl_b32 s54, s64, 10
	s_add_u32 s20, s60, 0x80
	s_addc_u32 s21, s61, 0
	s_lshl_b64 s[10:11], s[10:11], 1
	s_add_u32 s60, s20, s10
	s_addc_u32 s61, s21, s11
	s_lshl_b64 s[12:13], s[12:13], 1
	s_add_u32 s63, s20, s12
	s_addc_u32 s64, s21, s13
	s_add_u32 s22, s22, 0x80
	s_addc_u32 s23, s23, 0
	s_lshl_b64 s[14:15], s[14:15], 1
	s_add_u32 s74, s22, s14
	s_addc_u32 s75, s23, s15
	s_lshl_b64 s[16:17], s[16:17], 1
	s_add_u32 s76, s22, s16
	v_and_b32_e32 v3, 63, v2
	v_and_b32_e32 v130, 31, v2
	s_addc_u32 s77, s23, s17
	s_lshl_b64 s[18:19], s[18:19], 1
	v_lshrrev_b32_e32 v133, 5, v3
	v_lshrrev_b32_e32 v3, 2, v2
	v_bfe_u32 v2, v2, 2, 2
	v_or_b32_e32 v4, s3, v130
	s_add_u32 s78, s22, s18
	v_lshlrev_b32_e32 v138, 6, v4
	v_or_b32_e32 v4, s5, v130
	v_bitop3_b32 v2, v133, v2, 2 bitop3:0x36
	s_addc_u32 s79, s23, s19
	s_lshl_b64 s[20:21], s[6:7], 1
	v_lshlrev_b32_e32 v147, 6, v4
	v_bitop3_b32 v3, v133, v3, 3 bitop3:0x78
	v_lshlrev_b32_e32 v143, 4, v2
	s_add_u32 s6, s22, s20
	v_mov_b32_e32 v2, 0
	v_or_b32_e32 v141, 0x4000, v147
	v_lshlrev_b32_e32 v145, 4, v3
	s_addc_u32 s7, s23, s21
	s_mov_b32 s80, 0
	s_mov_b64 s[22:23], 0
	v_mov_b32_e32 v3, v2
	v_mov_b32_e32 v4, v2
	v_mov_b32_e32 v5, v2
	v_mov_b32_e32 v6, v2
	v_mov_b32_e32 v7, v2
	v_mov_b32_e32 v8, v2
	v_mov_b32_e32 v9, v2
	v_mov_b32_e32 v10, v2
	v_mov_b32_e32 v11, v2
	v_mov_b32_e32 v12, v2
	v_mov_b32_e32 v13, v2
	v_mov_b32_e32 v14, v2
	v_mov_b32_e32 v15, v2
	v_mov_b32_e32 v16, v2
	v_mov_b32_e32 v17, v2
	v_mov_b32_e32 v18, v2
	v_mov_b32_e32 v19, v2
	v_mov_b32_e32 v20, v2
	v_mov_b32_e32 v21, v2
	v_mov_b32_e32 v22, v2
	v_mov_b32_e32 v23, v2
	v_mov_b32_e32 v24, v2
	v_mov_b32_e32 v25, v2
	v_mov_b32_e32 v26, v2
	v_mov_b32_e32 v27, v2
	v_mov_b32_e32 v28, v2
	v_mov_b32_e32 v29, v2
	v_mov_b32_e32 v30, v2
	v_mov_b32_e32 v31, v2
	v_mov_b32_e32 v32, v2
	v_mov_b32_e32 v33, v2
	v_mov_b32_e32 v34, v2
	v_mov_b32_e32 v35, v2
	v_mov_b32_e32 v36, v2
	v_mov_b32_e32 v37, v2
	v_mov_b32_e32 v38, v2
	v_mov_b32_e32 v39, v2
	v_mov_b32_e32 v40, v2
	v_mov_b32_e32 v41, v2
	v_mov_b32_e32 v42, v2
	v_mov_b32_e32 v43, v2
	v_mov_b32_e32 v44, v2
	v_mov_b32_e32 v45, v2
	v_mov_b32_e32 v46, v2
	v_mov_b32_e32 v47, v2
	v_mov_b32_e32 v48, v2
	v_mov_b32_e32 v49, v2
	v_mov_b32_e32 v50, v2
	v_mov_b32_e32 v51, v2
	v_mov_b32_e32 v52, v2
	v_mov_b32_e32 v53, v2
	v_mov_b32_e32 v54, v2
	v_mov_b32_e32 v55, v2
	v_mov_b32_e32 v56, v2
	v_mov_b32_e32 v57, v2
	v_mov_b32_e32 v58, v2
	v_mov_b32_e32 v59, v2
	v_mov_b32_e32 v60, v2
	v_mov_b32_e32 v61, v2
	v_mov_b32_e32 v62, v2
	v_mov_b32_e32 v63, v2
	v_mov_b32_e32 v64, v2
	v_mov_b32_e32 v65, v2
	v_mov_b32_e32 v66, v2
	v_mov_b32_e32 v67, v2
	v_mov_b32_e32 v68, v2
	v_mov_b32_e32 v69, v2
	v_mov_b32_e32 v70, v2
	v_mov_b32_e32 v71, v2
	v_mov_b32_e32 v72, v2
	v_mov_b32_e32 v73, v2
	v_mov_b32_e32 v74, v2
	v_mov_b32_e32 v75, v2
	v_mov_b32_e32 v76, v2
	v_mov_b32_e32 v77, v2
	v_mov_b32_e32 v78, v2
	v_mov_b32_e32 v79, v2
	v_mov_b32_e32 v80, v2
	v_mov_b32_e32 v81, v2
	v_mov_b32_e32 v82, v2
	v_mov_b32_e32 v83, v2
	v_mov_b32_e32 v84, v2
	v_mov_b32_e32 v85, v2
	v_mov_b32_e32 v86, v2
	v_mov_b32_e32 v87, v2
	v_mov_b32_e32 v88, v2
	v_mov_b32_e32 v89, v2
	v_mov_b32_e32 v90, v2
	v_mov_b32_e32 v91, v2
	v_mov_b32_e32 v92, v2
	v_mov_b32_e32 v93, v2
	v_mov_b32_e32 v94, v2
	v_mov_b32_e32 v95, v2
	v_mov_b32_e32 v96, v2
	v_mov_b32_e32 v97, v2
	v_mov_b32_e32 v98, v2
	v_mov_b32_e32 v99, v2
	v_mov_b32_e32 v100, v2
	v_mov_b32_e32 v101, v2
	v_mov_b32_e32 v102, v2
	v_mov_b32_e32 v103, v2
	v_mov_b32_e32 v104, v2
	v_mov_b32_e32 v105, v2
	v_mov_b32_e32 v106, v2
	v_mov_b32_e32 v107, v2
	v_mov_b32_e32 v108, v2
	v_mov_b32_e32 v109, v2
	v_mov_b32_e32 v110, v2
	v_mov_b32_e32 v111, v2
	v_mov_b32_e32 v112, v2
	v_mov_b32_e32 v113, v2
	v_mov_b32_e32 v114, v2
	v_mov_b32_e32 v115, v2
	v_mov_b32_e32 v116, v2
	v_mov_b32_e32 v117, v2
	v_mov_b32_e32 v118, v2
	v_mov_b32_e32 v119, v2
	v_mov_b32_e32 v120, v2
	v_mov_b32_e32 v121, v2
	v_mov_b32_e32 v122, v2
	v_mov_b32_e32 v123, v2
	v_mov_b32_e32 v124, v2
	v_mov_b32_e32 v125, v2
	v_mov_b32_e32 v126, v2
	v_mov_b32_e32 v127, v2
	v_mov_b32_e32 v128, v2
	v_mov_b32_e32 v129, v2
	v_lshlrev_b32_e32 v254, 4, v200
.LBB0_118:
	s_cmp_gt_i32 s80, 0
	s_cselect_b32 s81, -1, 2
	s_add_i32 s81, s81, s80
	s_mulk_i32 s81, 0x6000
	s_add_u32 s82, s6, s22
	s_addc_u32 s83, s7, s23
	s_add_i32 s84, s59, s81
	s_cmp_eq_u32 s22, 0
	s_cbranch_scc1 .Lhy4_first_up
	s_waitcnt vmcnt(0)
	s_barrier
	s_add_i32 s98, s80, 1
	s_cmp_lg_u32 s80, 2
	s_cselect_b32 s98, s98, 0
	s_mul_i32 s98, s98, 0x6000
	s_add_i32 s99, s59, s98
	v_add_u32_e32 v238, s99, v254
	ds_write_b128 v238, v[214:217]
	s_add_i32 s99, s58, s98
	v_add_u32_e32 v255, s99, v254
	ds_write_b128 v255, v[218:221]
	s_add_i32 s99, s57, s98
	v_add_u32_e32 v238, s99, v254
	ds_write_b128 v238, v[222:225]
	s_add_i32 s99, s56, s98
	v_add_u32_e32 v255, s99, v254
	ds_write_b128 v255, v[226:229]
	s_add_i32 s99, s55, s98
	s_addk_i32 s99, 0x4000
	v_add_u32_e32 v238, s99, v254
	ds_write_b128 v238, v[230:233]
	s_add_i32 s99, s54, s98
	s_addk_i32 s99, 0x4000
	v_add_u32_e32 v255, s99, v254
	ds_write_b128 v255, v[234:237]
	s_branch .Lhy4_issue_up

; DEV f32x16 mfma(bf16x8 a, bf16x8 b, f32x16 c) { return __builtin_amdgcn_mfma_f32_32x32x16_bf16(a, b, c, 0, 0, 0); }
;     ...
;     if (kt + 2 < nk) { int s2 = stg + 2; if (s2 >= 3) s2 -= 3; g2_issue<MI>(ag + (size_t)(kt + 2) * 32, bg + (size_t)(kt + 2) * 32, lda, ldb, voffa, voffb, lds + s2 * G2_STAGE, w); }
;     const unsigned so = (unsigned)(stg * G2_STAGE);
;     __builtin_amdgcn_s_setprio(1);
; #pragma unroll
;     for (int ks = 0; ks < 2; ++ks) {
;       const unsigned aa = (ks ? la1 : la0) + so, bb = (ks ? lb1 : lb0) + so;
;       bf16x8 fb0, fb1, fa0, fa1, fa2, fa3;
;       asm volatile("ds_read_b128 %0, %1" : "=v"(fb0) : "v"(bb));
;       asm volatile("ds_read_b128 %0, %1 offset:2048" : "=v"(fb1) : "v"(bb));
;       asm volatile("ds_read_b128 %0, %1" : "=v"(fa0) : "v"(aa));
;       asm volatile("ds_read_b128 %0, %1 offset:2048" : "=v"(fa1) : "v"(aa));
;       if constexpr (MI == 4) {
;         asm volatile("ds_read_b128 %0, %1 offset:4096" : "=v"(fa2) : "v"(aa));
;         asm volatile("ds_read_b128 %0, %1 offset:6144" : "=v"(fa3) : "v"(aa));
;         __builtin_amdgcn_sched_barrier(0);
;         asm volatile("s_waitcnt lgkmcnt(3)" : "+v"(fb0), "+v"(fb1), "+v"(fa0));
;         acc[0][0][0] = mfma(fa0, fb0, acc[0][0][0]); acc[0][0][1] = mfma(fa0, fb1, acc[0][0][1]); __builtin_amdgcn_sched_barrier(0);
;         asm volatile("s_waitcnt lgkmcnt(2)" : "+v"(fa1));
;         acc[0][1][0] = mfma(fa1, fb0, acc[0][1][0]); acc[0][1][1] = mfma(fa1, fb1, acc[0][1][1]); __builtin_amdgcn_sched_barrier(0);
;         asm volatile("s_waitcnt lgkmcnt(1)" : "+v"(fa2));
;         acc[MI / 2 - 1][0][0] = mfma(fa2, fb0, acc[MI / 2 - 1][0][0]); acc[MI / 2 - 1][0][1] = mfma(fa2, fb1, acc[MI / 2 - 1][0][1]); __builtin_amdgcn_sched_barrier(0);
;         asm volatile("s_waitcnt lgkmcnt(0)" : "+v"(fa3));
;         acc[MI / 2 - 1][1][0] = mfma(fa3, fb0, acc[MI / 2 - 1][1][0]); acc[MI / 2 - 1][1][1] = mfma(fa3, fb1, acc[MI / 2 - 1][1][1]); __builtin_amdgcn_sched_barrier(0);
.Lhy4_issue_up:
	s_mul_i32 s99, s80, 0x6000
	s_setprio 1
	v_add_u32_e32 v149, s99, v138
	v_add_u32_e32 v176, s99, v141
	v_add_u32_e32 v172, v149, v145
	v_add_u32_e32 v156, v176, v145
	ds_read_b128 v[152:155], v156
	ds_read_b128 v[156:159], v156 offset:2048
	ds_read_b128 v[160:163], v172
	ds_read_b128 v[164:167], v172 offset:2048
	ds_read_b128 v[168:171], v172 offset:4096
	ds_read_b128 v[172:175], v172 offset:6144
	v_add_u32_e32 v238, v176, v143
	v_add_u32_e32 v149, v149, v143
	ds_read_b128 v[180:183], v238
	ds_read_b128 v[184:187], v238 offset:2048
	ds_read_b128 v[188:191], v149
	ds_read_b128 v[242:245], v149 offset:2048
	ds_read_b128 v[246:249], v149 offset:4096
	ds_read_b128 v[250:253], v149 offset:6144
	s_cmpk_eq_i32 s22, 0xf80
	s_cbranch_scc1 .Lhy4_noissueE_up
	s_nop 0
	s_waitcnt lgkmcnt(9)
	s_nop 0
	v_mfma_f32_32x32x16_bf16 v[114:129], v[160:163], v[152:155], v[114:129]
	v_mfma_f32_32x32x16_bf16 v[98:113], v[160:163], v[156:159], v[98:113]
	s_mov_b32 m0, s84
	s_nop 0
	global_load_lds_dwordx4 v1, s[82:83]
	global_load_dwordx4 v[214:217], v1, s[82:83] offset:64
	s_waitcnt lgkmcnt(8)
	s_nop 0
	v_mfma_f32_32x32x16_bf16 v[82:97], v[164:167], v[152:155], v[82:97]
	v_mfma_f32_32x32x16_bf16 v[66:81], v[164:167], v[156:159], v[66:81]
	s_add_u32 s82, s78, s22
	s_addc_u32 s83, s79, s23
	s_add_i32 s84, s58, s81
	s_mov_b32 m0, s84
	s_nop 0
	global_load_lds_dwordx4 v1, s[82:83]
	global_load_dwordx4 v[218:221], v1, s[82:83] offset:64
	s_waitcnt lgkmcnt(7)
	s_nop 0
	v_mfma_f32_32x32x16_bf16 v[50:65], v[168:171], v[152:155], v[50:65]
	v_mfma_f32_32x32x16_bf16 v[34:49], v[168:171], v[156:159], v[34:49]
	s_add_u32 s82, s76, s22
	s_addc_u32 s83, s77, s23
	s_add_i32 s84, s57, s81
	s_mov_b32 m0, s84
	s_nop 0
	global_load_lds_dwordx4 v1, s[82:83]
	global_load_dwordx4 v[222:225], v1, s[82:83] offset:64
	s_waitcnt lgkmcnt(6)
	s_nop 0
	v_mfma_f32_32x32x16_bf16 v[18:33], v[172:175], v[152:155], v[18:33]
	v_mfma_f32_32x32x16_bf16 v[2:17], v[172:175], v[156:159], v[2:17]
	s_branch .Lhy4_afterE_up

; DEV f32x16 mfma(bf16x8 a, bf16x8 b, f32x16 c) { return __builtin_amdgcn_mfma_f32_32x32x16_bf16(a, b, c, 0, 0, 0); }
;     ...
;     if (kt + 1 < nk) { if (MI == 4) asm volatile("s_waitcnt vmcnt(6)" ::: "memory"); else asm volatile("s_waitcnt vmcnt(4)" ::: "memory"); } else asm volatile("s_waitcnt vmcnt(0)" ::: "memory");
;     __builtin_amdgcn_s_barrier();
;     if (kt + 2 < nk) { int s2 = stg + 2; if (s2 >= 3) s2 -= 3; g2_issue<MI>(ag + (size_t)(kt + 2) * 32, bg + (size_t)(kt + 2) * 32, lda, ldb, voffa, voffb, lds + s2 * G2_STAGE, w); }
;     const unsigned so = (unsigned)(stg * G2_STAGE);
;     __builtin_amdgcn_s_setprio(1);
; #pragma unroll
;     for (int ks = 0; ks < 2; ++ks) {
;       const unsigned aa = (ks ? la1 : la0) + so, bb = (ks ? lb1 : lb0) + so;
;       bf16x8 fb0, fb1, fa0, fa1, fa2, fa3;
;       asm volatile("ds_read_b128 %0, %1" : "=v"(fb0) : "v"(bb));
;       asm volatile("ds_read_b128 %0, %1 offset:2048" : "=v"(fb1) : "v"(bb));
;       asm volatile("ds_read_b128 %0, %1" : "=v"(fa0) : "v"(aa));
;       asm volatile("ds_read_b128 %0, %1 offset:2048" : "=v"(fa1) : "v"(aa));
;       if constexpr (MI == 4) {
;         asm volatile("ds_read_b128 %0, %1 offset:4096" : "=v"(fa2) : "v"(aa));
;         asm volatile("ds_read_b128 %0, %1 offset:6144" : "=v"(fa3) : "v"(aa));
;         __builtin_amdgcn_sched_barrier(0);
;         asm volatile("s_waitcnt lgkmcnt(3)" : "+v"(fb0), "+v"(fb1), "+v"(fa0));
;         acc[0][0][0] = mfma(fa0, fb0, acc[0][0][0]); acc[0][0][1] = mfma(fa0, fb1, acc[0][0][1]); __builtin_amdgcn_sched_barrier(0);
;         asm volatile("s_waitcnt lgkmcnt(2)" : "+v"(fa1));
;         acc[0][1][0] = mfma(fa1, fb0, acc[0][1][0]); acc[0][1][1] = mfma(fa1, fb1, acc[0][1][1]); __builtin_amdgcn_sched_barrier(0);
;         asm volatile("s_waitcnt lgkmcnt(1)" : "+v"(fa2));
;         acc[MI / 2 - 1][0][0] = mfma(fa2, fb0, acc[MI / 2 - 1][0][0]); acc[MI / 2 - 1][0][1] = mfma(fa2, fb1, acc[MI / 2 - 1][0][1]); __builtin_amdgcn_sched_barrier(0);
;         asm volatile("s_waitcnt lgkmcnt(0)" : "+v"(fa3));
;         acc[MI / 2 - 1][1][0] = mfma(fa3, fb0, acc[MI / 2 - 1][1][0]); acc[MI / 2 - 1][1][1] = mfma(fa3, fb1, acc[MI / 2 - 1][1][1]); __builtin_amdgcn_sched_barrier(0);
.Lhy4_afterE_up:
	s_nop 0
	s_waitcnt lgkmcnt(3)
	s_nop 0
	v_mfma_f32_32x32x16_bf16 v[114:129], v[188:191], v[180:183], v[114:129]
	v_mfma_f32_32x32x16_bf16 v[98:113], v[188:191], v[184:187], v[98:113]
	s_waitcnt lgkmcnt(2)
	s_nop 0
	v_mfma_f32_32x32x16_bf16 v[82:97], v[242:245], v[180:183], v[82:97]
	v_mfma_f32_32x32x16_bf16 v[66:81], v[242:245], v[184:187], v[66:81]
	s_waitcnt lgkmcnt(1)
	s_nop 0
	v_mfma_f32_32x32x16_bf16 v[50:65], v[246:249], v[180:183], v[50:65]
	v_mfma_f32_32x32x16_bf16 v[34:49], v[246:249], v[184:187], v[34:49]
	s_waitcnt lgkmcnt(0)
	s_nop 0
	v_mfma_f32_32x32x16_bf16 v[18:33], v[250:253], v[180:183], v[18:33]
	v_mfma_f32_32x32x16_bf16 v[2:17], v[250:253], v[184:187], v[2:17]
	s_setprio 0
	s_add_i32 s98, s80, 1
	s_cmp_lg_u32 s80, 2
	s_cselect_b32 s80, s98, 0
	s_waitcnt vmcnt(6)
	s_barrier
	s_mul_i32 s99, s80, 0x6000
	s_setprio 1
	v_add_u32_e32 v149, s99, v138
	v_add_u32_e32 v176, s99, v141
	v_add_u32_e32 v172, v149, v145
	v_add_u32_e32 v156, v176, v145
	ds_read_b128 v[152:155], v156
	ds_read_b128 v[156:159], v156 offset:2048
	ds_read_b128 v[160:163], v172
	ds_read_b128 v[164:167], v172 offset:2048
	ds_read_b128 v[168:171], v172 offset:4096
	ds_read_b128 v[172:175], v172 offset:6144
	v_add_u32_e32 v238, v176, v143
	v_add_u32_e32 v149, v149, v143
	ds_read_b128 v[180:183], v238
	ds_read_b128 v[184:187], v238 offset:2048
	ds_read_b128 v[188:191], v149
	ds_read_b128 v[242:245], v149 offset:2048
	ds_read_b128 v[246:249], v149 offset:4096
	ds_read_b128 v[250:253], v149 offset:6144
	s_cmpk_eq_i32 s22, 0xf80
	s_cbranch_scc1 .Lhy4_noissueO_up
	s_nop 0
	s_waitcnt lgkmcnt(9)
	s_nop 0
	v_mfma_f32_32x32x16_bf16 v[114:129], v[160:163], v[152:155], v[114:129]
	v_mfma_f32_32x32x16_bf16 v[98:113], v[160:163], v[156:159], v[98:113]
	s_add_u32 s82, s74, s22
	s_addc_u32 s83, s75, s23
	s_add_i32 s84, s56, s81
	s_addk_i32 s81, 0x4000
	s_mov_b32 m0, s84
	s_nop 0
	global_load_lds_dwordx4 v1, s[82:83]
	global_load_dwordx4 v[226:229], v1, s[82:83] offset:64
	s_waitcnt lgkmcnt(8)
	s_nop 0
	v_mfma_f32_32x32x16_bf16 v[82:97], v[164:167], v[152:155], v[82:97]
	v_mfma_f32_32x32x16_bf16 v[66:81], v[164:167], v[156:159], v[66:81]
	s_add_u32 s82, s63, s22
	s_addc_u32 s83, s64, s23
	s_add_i32 s84, s81, s55
	s_mov_b32 m0, s84
	s_nop 0
	global_load_lds_dwordx4 v1, s[82:83]
	global_load_dwordx4 v[230:233], v1, s[82:83] offset:64
	s_waitcnt lgkmcnt(7)
	s_nop 0
	v_mfma_f32_32x32x16_bf16 v[50:65], v[168:171], v[152:155], v[50:65]
	v_mfma_f32_32x32x16_bf16 v[34:49], v[168:171], v[156:159], v[34:49]
	s_add_u32 s82, s60, s22
	s_addc_u32 s83, s61, s23
	s_add_i32 s81, s81, s54
	s_mov_b32 m0, s81
	s_nop 0
	global_load_lds_dwordx4 v1, s[82:83]
	global_load_dwordx4 v[234:237], v1, s[82:83] offset:64
	s_waitcnt lgkmcnt(6)
	s_nop 0
	v_mfma_f32_32x32x16_bf16 v[18:33], v[172:175], v[152:155], v[18:33]
	v_mfma_f32_32x32x16_bf16 v[2:17], v[172:175], v[156:159], v[2:17]
	s_branch .Lhy4_afterO_up

; DEV f32x16 mfma(bf16x8 a, bf16x8 b, f32x16 c) { return __builtin_amdgcn_mfma_f32_32x32x16_bf16(a, b, c, 0, 0, 0); }
;     ...
;         acc[0][1][0] = mfma(fa1, fb0, acc[0][1][0]); acc[0][1][1] = mfma(fa1, fb1, acc[0][1][1]); __builtin_amdgcn_sched_barrier(0);
;         asm volatile("s_waitcnt lgkmcnt(1)" : "+v"(fa2));
;         acc[MI / 2 - 1][0][0] = mfma(fa2, fb0, acc[MI / 2 - 1][0][0]); acc[MI / 2 - 1][0][1] = mfma(fa2, fb1, acc[MI / 2 - 1][0][1]); __builtin_amdgcn_sched_barrier(0);
;         asm volatile("s_waitcnt lgkmcnt(0)" : "+v"(fa3));
;         acc[MI / 2 - 1][1][0] = mfma(fa3, fb0, acc[MI / 2 - 1][1][0]); acc[MI / 2 - 1][1][1] = mfma(fa3, fb1, acc[MI / 2 - 1][1][1]); __builtin_amdgcn_sched_barrier(0);
;       } else {
;         __builtin_amdgcn_sched_barrier(0);
;         asm volatile("s_waitcnt lgkmcnt(1)" : "+v"(fb0), "+v"(fb1), "+v"(fa0));
;         acc[0][0][0] = mfma(fa0, fb0, acc[0][0][0]); acc[0][0][1] = mfma(fa0, fb1, acc[0][0][1]); __builtin_amdgcn_sched_barrier(0);
;         asm volatile("s_waitcnt lgkmcnt(0)" : "+v"(fa1));
;         acc[0][1][0] = mfma(fa1, fb0, acc[0][1][0]); acc[0][1][1] = mfma(fa1, fb1, acc[0][1][1]); __builtin_amdgcn_sched_barrier(0);
;       }
;     }
;     __builtin_amdgcn_s_setprio(0);
;     stg = stg == 2 ? 0 : stg + 1;
;   }
;   __syncthreads();
;   if (has_next) {
;     const bf16_t* agn = uni_ptr(A + (size_t)m0n * lda + kbeg);
;     const bf16_t* bgn = uni_ptr(Bt + (size_t)n0n * ldb + kbeg);
;     g2_issue<MI>(agn, bgn, lda, ldb, voffa, voffb, lds, w);
;     g2_issue<MI>(agn + 32, bgn + 32, lda, ldb, voffa, voffb, lds + G2_STAGE, w);
.Lhy4_afterO_up:
	s_nop 0
	s_waitcnt lgkmcnt(3)
	s_nop 0
	v_mfma_f32_32x32x16_bf16 v[114:129], v[188:191], v[180:183], v[114:129]
	v_mfma_f32_32x32x16_bf16 v[98:113], v[188:191], v[184:187], v[98:113]
	s_waitcnt lgkmcnt(2)
	s_nop 0
	v_mfma_f32_32x32x16_bf16 v[82:97], v[242:245], v[180:183], v[82:97]
	v_mfma_f32_32x32x16_bf16 v[66:81], v[242:245], v[184:187], v[66:81]
	s_waitcnt lgkmcnt(1)
	s_nop 0
	v_mfma_f32_32x32x16_bf16 v[50:65], v[246:249], v[180:183], v[50:65]
	v_mfma_f32_32x32x16_bf16 v[34:49], v[246:249], v[184:187], v[34:49]
	s_waitcnt lgkmcnt(0)
	s_nop 0
	v_mfma_f32_32x32x16_bf16 v[18:33], v[250:253], v[180:183], v[18:33]
	v_mfma_f32_32x32x16_bf16 v[2:17], v[250:253], v[184:187], v[2:17]
	s_add_i32 s98, s80, 1
	s_cmp_lg_u32 s80, 2
	s_cselect_b32 s80, s98, 0
	s_add_u32 s22, s22, 0x80
	s_addc_u32 s23, s23, 0
	s_cmpk_eq_i32 s22, 0x1000
	s_cbranch_scc0 .LBB0_118
	s_setprio 0
	s_and_b64 vcc, exec, s[8:9]
	s_waitcnt lgkmcnt(0)
	s_barrier
	s_cbranch_vccz .LBB0_109
	s_lshl_b32 s6, s52, 8
	s_ashr_i32 s7, s6, 31
	s_lshl_b32 s8, s53, 7
	s_lshl_b64 s[6:7], s[6:7], 12
	s_add_u32 s22, s26, s6
	s_addc_u32 s23, s27, s7
	s_ashr_i32 s9, s8, 31
	s_lshl_b64 s[6:7], s[8:9], 12
	s_add_u32 s60, s28, s6
	s_addc_u32 s61, s30, s7
	s_add_u32 s6, s22, s20
	s_addc_u32 s7, s23, s21
	s_add_u32 s8, s22, s18
	s_addc_u32 s9, s23, s19
	s_add_u32 s16, s22, s16
	s_addc_u32 s17, s23, s17
	s_add_u32 s14, s22, s14
	s_mov_b32 m0, s59
	s_nop 0
	global_load_lds_dwordx4 v1, s[6:7]
	s_addc_u32 s15, s23, s15
	s_mov_b32 m0, s58
	s_nop 0
	global_load_lds_dwordx4 v1, s[8:9]
	s_add_u32 s12, s60, s12
	s_mov_b32 m0, s57
	s_nop 0
	global_load_lds_dwordx4 v1, s[16:17]
	s_addc_u32 s13, s61, s13
	s_add_i32 s18, s55, 0x4000
	s_mov_b32 m0, s56
	s_nop 0
	global_load_lds_dwordx4 v1, s[14:15]
	s_add_u32 s10, s60, s10
	s_mov_b32 m0, s18
	s_nop 0
	global_load_lds_dwordx4 v1, s[12:13]
	s_addc_u32 s11, s61, s11
	s_add_i32 s18, s54, 0x4000
	s_add_u32 s6, s6, 64
	s_mov_b32 m0, s18
	s_nop 0
	global_load_lds_dwordx4 v1, s[10:11]
	s_addc_u32 s7, s7, 0
	s_add_i32 s18, s59, 0x6000
	s_mov_b32 m0, s18
	s_nop 0
	global_load_lds_dwordx4 v1, s[6:7]
	s_add_u32 s6, s8, 64
	s_addc_u32 s7, s9, 0
	s_add_i32 s8, s58, 0x6000
	s_mov_b32 m0, s8
	s_nop 0
	global_load_lds_dwordx4 v1, s[6:7]
	s_add_u32 s6, s16, 64
	s_addc_u32 s7, s17, 0
	s_add_i32 s8, s57, 0x6000
	s_mov_b32 m0, s8
	s_nop 0
	global_load_lds_dwordx4 v1, s[6:7]
	s_add_u32 s6, s14, 64
	s_addc_u32 s7, s15, 0
	s_add_i32 s8, s56, 0x6000
	s_mov_b32 m0, s8
	s_nop 0
	global_load_lds_dwordx4 v1, s[6:7]
	s_add_u32 s6, s12, 64
	s_addc_u32 s7, s13, 0
	s_add_i32 s55, s55, 0xa000
	s_mov_b32 m0, s55
	s_nop 0
	global_load_lds_dwordx4 v1, s[6:7]
	s_add_u32 s6, s10, 64
	s_addc_u32 s7, s11, 0
	s_add_i32 s54, s54, 0xa000
	s_mov_b32 m0, s54
	s_nop 0
	global_load_lds_dwordx4 v1, s[6:7]
	s_branch .LBB0_109

; DEV int otid() { int t = threadIdx.x; asm volatile("" : "+v"(t)); return t; }
;   const int tid = otid(), lane = tid & 63, w = __builtin_amdgcn_readfirstlane(tid >> 6), wm = w >> 1, wn = w & 1, r32 = lane & 31, hh = lane >> 5;
;   f32x16 acc[MI / 2][2][2];
; #pragma unroll
;   for (int h = 0; h < MI / 2; ++h) { acc[h][0][0] = zero16(); acc[h][0][1] = zero16(); acc[h][1][0] = zero16(); acc[h][1][1] = zero16(); }
;   const int lrow = lane >> 2, lp = (lane & 3) ^ ((lane >> 4) & 3);
;   const bf16_t* ag = uni_ptr(A + (size_t)m0 * lda + kbeg);
;   const bf16_t* bg = uni_ptr(Bt + (size_t)n0 * ldb + kbeg);
;   const unsigned voffa = ((unsigned)lrow * (unsigned)lda + (unsigned)lp * 8u) * 2u;
;   const unsigned voffb = ((unsigned)lrow * (unsigned)ldb + (unsigned)lp * 8u) * 2u;
;   const int nk = (kend - kbeg) >> 5;
;   if (!pre) {
;     asm volatile("s_waitcnt vmcnt(0)" ::: "memory");
;     g2_issue<MI>(ag, bg, lda, ldb, voffa, voffb, lds, w);
;     if (nk > 1) g2_issue<MI>(ag + 32, bg + 32, lda, ldb, voffa, voffb, lds + G2_STAGE, w);
;   }
;   const int key = (r32 >> 2) & 3;
;   const int aoff = (wm * (MI * 32) + r32) * 64;
;   const int boff = 16384 + (wn * 64 + r32) * 64;
;   const int p0 = ((0 + hh) ^ key) * 16, p1 = ((2 + hh) ^ key) * 16;
;   const unsigned lbase = (unsigned)(size_t)lds;
;   const unsigned la0 = lbase + aoff + p0, la1 = lbase + aoff + p1, lb0 = lbase + boff + p0, lb1 = lbase + boff + p1;
;   int stg = 0;
.LBB0_156:
	s_xor_b64 s[0:1], s[8:9], -1
	s_and_b32 s3, s55, 0xffffff80
	s_and_b32 s5, s55, 64
	s_lshl_b32 s59, s54, 12
	s_lshl_b32 s58, s56, 10
	s_lshl_b32 s57, s57, 10
	s_lshl_b32 s56, s63, 10
	s_lshl_b32 s55, s54, 11
	s_lshl_b32 s54, s64, 10
	s_add_u32 s20, s60, 0x80
	s_addc_u32 s21, s61, 0
	s_lshl_b64 s[10:11], s[10:11], 1
	s_add_u32 s60, s20, s10
	s_addc_u32 s61, s21, s11
	s_lshl_b64 s[12:13], s[12:13], 1
	s_add_u32 s63, s20, s12
	s_addc_u32 s64, s21, s13
	s_add_u32 s22, s22, 0x80
	s_addc_u32 s23, s23, 0
	s_lshl_b64 s[14:15], s[14:15], 1
	s_add_u32 s74, s22, s14
	s_addc_u32 s75, s23, s15
	s_lshl_b64 s[16:17], s[16:17], 1
	s_add_u32 s76, s22, s16
	v_and_b32_e32 v3, 63, v2
	v_and_b32_e32 v130, 31, v2
	s_addc_u32 s77, s23, s17
	s_lshl_b64 s[18:19], s[18:19], 1
	v_lshrrev_b32_e32 v133, 5, v3
	v_lshrrev_b32_e32 v3, 2, v2
	v_bfe_u32 v2, v2, 2, 2
	v_or_b32_e32 v4, s3, v130
	s_add_u32 s78, s22, s18
	v_lshlrev_b32_e32 v138, 6, v4
	v_or_b32_e32 v4, s5, v130
	v_bitop3_b32 v2, v133, v2, 2 bitop3:0x36
	s_addc_u32 s79, s23, s19
	s_lshl_b64 s[20:21], s[6:7], 1
	v_lshlrev_b32_e32 v147, 6, v4
	v_bitop3_b32 v3, v133, v3, 3 bitop3:0x78
	v_lshlrev_b32_e32 v143, 4, v2
	s_add_u32 s6, s22, s20
	v_mov_b32_e32 v2, 0
	v_or_b32_e32 v141, 0x4000, v147
	v_lshlrev_b32_e32 v145, 4, v3
	s_addc_u32 s7, s23, s21
	s_mov_b32 s80, 0
	s_mov_b64 s[22:23], 0
	v_mov_b32_e32 v3, v2
	v_mov_b32_e32 v4, v2
	v_mov_b32_e32 v5, v2
	v_mov_b32_e32 v6, v2
	v_mov_b32_e32 v7, v2
	v_mov_b32_e32 v8, v2
	v_mov_b32_e32 v9, v2
	v_mov_b32_e32 v10, v2
	v_mov_b32_e32 v11, v2
	v_mov_b32_e32 v12, v2
	v_mov_b32_e32 v13, v2
	v_mov_b32_e32 v14, v2
	v_mov_b32_e32 v15, v2
	v_mov_b32_e32 v16, v2
	v_mov_b32_e32 v17, v2
	v_mov_b32_e32 v18, v2
	v_mov_b32_e32 v19, v2
	v_mov_b32_e32 v20, v2
	v_mov_b32_e32 v21, v2
	v_mov_b32_e32 v22, v2
	v_mov_b32_e32 v23, v2
	v_mov_b32_e32 v24, v2
	v_mov_b32_e32 v25, v2
	v_mov_b32_e32 v26, v2
	v_mov_b32_e32 v27, v2
	v_mov_b32_e32 v28, v2
	v_mov_b32_e32 v29, v2
	v_mov_b32_e32 v30, v2
	v_mov_b32_e32 v31, v2
	v_mov_b32_e32 v32, v2
	v_mov_b32_e32 v33, v2
	v_mov_b32_e32 v34, v2
	v_mov_b32_e32 v35, v2
	v_mov_b32_e32 v36, v2
	v_mov_b32_e32 v37, v2
	v_mov_b32_e32 v38, v2
	v_mov_b32_e32 v39, v2
	v_mov_b32_e32 v40, v2
	v_mov_b32_e32 v41, v2
	v_mov_b32_e32 v42, v2
	v_mov_b32_e32 v43, v2
	v_mov_b32_e32 v44, v2
	v_mov_b32_e32 v45, v2
	v_mov_b32_e32 v46, v2
	v_mov_b32_e32 v47, v2
	v_mov_b32_e32 v48, v2
	v_mov_b32_e32 v49, v2
	v_mov_b32_e32 v50, v2
	v_mov_b32_e32 v51, v2
	v_mov_b32_e32 v52, v2
	v_mov_b32_e32 v53, v2
	v_mov_b32_e32 v54, v2
	v_mov_b32_e32 v55, v2
	v_mov_b32_e32 v56, v2
	v_mov_b32_e32 v57, v2
	v_mov_b32_e32 v58, v2
	v_mov_b32_e32 v59, v2
	v_mov_b32_e32 v60, v2
	v_mov_b32_e32 v61, v2
	v_mov_b32_e32 v62, v2
	v_mov_b32_e32 v63, v2
	v_mov_b32_e32 v64, v2
	v_mov_b32_e32 v65, v2
	v_mov_b32_e32 v66, v2
	v_mov_b32_e32 v67, v2
	v_mov_b32_e32 v68, v2
	v_mov_b32_e32 v69, v2
	v_mov_b32_e32 v70, v2
	v_mov_b32_e32 v71, v2
	v_mov_b32_e32 v72, v2
	v_mov_b32_e32 v73, v2
	v_mov_b32_e32 v74, v2
	v_mov_b32_e32 v75, v2
	v_mov_b32_e32 v76, v2
	v_mov_b32_e32 v77, v2
	v_mov_b32_e32 v78, v2
	v_mov_b32_e32 v79, v2
	v_mov_b32_e32 v80, v2
	v_mov_b32_e32 v81, v2
	v_mov_b32_e32 v82, v2
	v_mov_b32_e32 v83, v2
	v_mov_b32_e32 v84, v2
	v_mov_b32_e32 v85, v2
	v_mov_b32_e32 v86, v2
	v_mov_b32_e32 v87, v2
	v_mov_b32_e32 v88, v2
	v_mov_b32_e32 v89, v2
	v_mov_b32_e32 v90, v2
	v_mov_b32_e32 v91, v2
	v_mov_b32_e32 v92, v2
	v_mov_b32_e32 v93, v2
	v_mov_b32_e32 v94, v2
	v_mov_b32_e32 v95, v2
	v_mov_b32_e32 v96, v2
	v_mov_b32_e32 v97, v2
	v_mov_b32_e32 v98, v2
	v_mov_b32_e32 v99, v2
	v_mov_b32_e32 v100, v2
	v_mov_b32_e32 v101, v2
	v_mov_b32_e32 v102, v2
	v_mov_b32_e32 v103, v2
	v_mov_b32_e32 v104, v2
	v_mov_b32_e32 v105, v2
	v_mov_b32_e32 v106, v2
	v_mov_b32_e32 v107, v2
	v_mov_b32_e32 v108, v2
	v_mov_b32_e32 v109, v2
	v_mov_b32_e32 v110, v2
	v_mov_b32_e32 v111, v2
	v_mov_b32_e32 v112, v2
	v_mov_b32_e32 v113, v2
	v_mov_b32_e32 v114, v2
	v_mov_b32_e32 v115, v2
	v_mov_b32_e32 v116, v2
	v_mov_b32_e32 v117, v2
	v_mov_b32_e32 v118, v2
	v_mov_b32_e32 v119, v2
	v_mov_b32_e32 v120, v2
	v_mov_b32_e32 v121, v2
	v_mov_b32_e32 v122, v2
	v_mov_b32_e32 v123, v2
	v_mov_b32_e32 v124, v2
	v_mov_b32_e32 v125, v2
	v_mov_b32_e32 v126, v2
	v_mov_b32_e32 v127, v2
	v_mov_b32_e32 v128, v2
	v_mov_b32_e32 v129, v2
	v_lshlrev_b32_e32 v254, 4, v200

; DEV f32x16 mfma(bf16x8 a, bf16x8 b, f32x16 c) { return __builtin_amdgcn_mfma_f32_32x32x16_bf16(a, b, c, 0, 0, 0); }
;     ...
;         acc[0][1][0] = mfma(fa1, fb0, acc[0][1][0]); acc[0][1][1] = mfma(fa1, fb1, acc[0][1][1]); __builtin_amdgcn_sched_barrier(0);
;         asm volatile("s_waitcnt lgkmcnt(1)" : "+v"(fa2));
;         acc[MI / 2 - 1][0][0] = mfma(fa2, fb0, acc[MI / 2 - 1][0][0]); acc[MI / 2 - 1][0][1] = mfma(fa2, fb1, acc[MI / 2 - 1][0][1]); __builtin_amdgcn_sched_barrier(0);
;         asm volatile("s_waitcnt lgkmcnt(0)" : "+v"(fa3));
;         acc[MI / 2 - 1][1][0] = mfma(fa3, fb0, acc[MI / 2 - 1][1][0]); acc[MI / 2 - 1][1][1] = mfma(fa3, fb1, acc[MI / 2 - 1][1][1]); __builtin_amdgcn_sched_barrier(0);
;       } else {
;         __builtin_amdgcn_sched_barrier(0);
;         asm volatile("s_waitcnt lgkmcnt(1)" : "+v"(fb0), "+v"(fb1), "+v"(fa0));
;         acc[0][0][0] = mfma(fa0, fb0, acc[0][0][0]); acc[0][0][1] = mfma(fa0, fb1, acc[0][0][1]); __builtin_amdgcn_sched_barrier(0);
;         asm volatile("s_waitcnt lgkmcnt(0)" : "+v"(fa1));
;         acc[0][1][0] = mfma(fa1, fb0, acc[0][1][0]); acc[0][1][1] = mfma(fa1, fb1, acc[0][1][1]); __builtin_amdgcn_sched_barrier(0);
;       }
;     }
;     __builtin_amdgcn_s_setprio(0);
;     stg = stg == 2 ? 0 : stg + 1;
;   }
;   __syncthreads();
;   if (has_next) {
;     const bf16_t* agn = uni_ptr(A + (size_t)m0n * lda + kbeg);
;     const bf16_t* bgn = uni_ptr(Bt + (size_t)n0n * ldb + kbeg);
;     g2_issue<MI>(agn, bgn, lda, ldb, voffa, voffb, lds, w);
;     g2_issue<MI>(agn + 32, bgn + 32, lda, ldb, voffa, voffb, lds + G2_STAGE, w);
.Lhy4_afterO_proj:
	s_nop 0
	s_waitcnt lgkmcnt(3)
	s_nop 0
	v_mfma_f32_32x32x16_bf16 v[114:129], v[188:191], v[180:183], v[114:129]
	v_mfma_f32_32x32x16_bf16 v[98:113], v[188:191], v[184:187], v[98:113]
	s_waitcnt lgkmcnt(2)
	s_nop 0
	v_mfma_f32_32x32x16_bf16 v[82:97], v[242:245], v[180:183], v[82:97]
	v_mfma_f32_32x32x16_bf16 v[66:81], v[242:245], v[184:187], v[66:81]
	s_waitcnt lgkmcnt(1)
	s_nop 0
	v_mfma_f32_32x32x16_bf16 v[50:65], v[246:249], v[180:183], v[50:65]
	v_mfma_f32_32x32x16_bf16 v[34:49], v[246:249], v[184:187], v[34:49]
	s_waitcnt lgkmcnt(0)
	s_nop 0
	v_mfma_f32_32x32x16_bf16 v[18:33], v[250:253], v[180:183], v[18:33]
	v_mfma_f32_32x32x16_bf16 v[2:17], v[250:253], v[184:187], v[2:17]
	s_add_i32 s98, s80, 1
	s_cmp_lg_u32 s80, 2
	s_cselect_b32 s80, s98, 0
	s_add_u32 s22, s22, 0x80
	s_addc_u32 s23, s23, 0
	s_cmpk_eq_i32 s22, 0x1000
	s_cbranch_scc0 .LBB0_157
	s_setprio 0
	s_and_b64 vcc, exec, s[8:9]
	s_waitcnt lgkmcnt(0)
	s_barrier
	s_cbranch_vccz .LBB0_145
	s_lshl_b32 s6, s25, 8
	s_ashr_i32 s7, s6, 31
	s_lshl_b32 s8, s26, 7
	s_lshl_b64 s[6:7], s[6:7], 12
	s_add_u32 s22, s27, s6
	s_addc_u32 s23, s28, s7
	s_ashr_i32 s9, s8, 31
	s_lshl_b64 s[6:7], s[8:9], 12
	s_add_u32 s60, s30, s6
	s_addc_u32 s61, s31, s7
	s_add_u32 s6, s22, s20
	s_addc_u32 s7, s23, s21
	s_add_u32 s8, s22, s18
	s_addc_u32 s9, s23, s19
	s_add_u32 s16, s22, s16
	s_addc_u32 s17, s23, s17
	s_add_u32 s14, s22, s14
	s_mov_b32 m0, s59
	s_nop 0
	global_load_lds_dwordx4 v1, s[6:7]
	s_addc_u32 s15, s23, s15
	s_mov_b32 m0, s58
	s_nop 0
	global_load_lds_dwordx4 v1, s[8:9]
	s_add_u32 s12, s60, s12
	s_mov_b32 m0, s57
	s_nop 0
	global_load_lds_dwordx4 v1, s[16:17]
	s_addc_u32 s13, s61, s13
	s_add_i32 s18, s55, 0x4000
	s_mov_b32 m0, s56
	s_nop 0
	global_load_lds_dwordx4 v1, s[14:15]
	s_add_u32 s10, s60, s10
	s_mov_b32 m0, s18
	s_nop 0
	global_load_lds_dwordx4 v1, s[12:13]
	s_addc_u32 s11, s61, s11
	s_add_i32 s18, s54, 0x4000
	s_add_u32 s6, s6, 64
	s_mov_b32 m0, s18
	s_nop 0
	global_load_lds_dwordx4 v1, s[10:11]
	s_addc_u32 s7, s7, 0
	s_add_i32 s18, s59, 0x6000
	s_mov_b32 m0, s18
	s_nop 0
	global_load_lds_dwordx4 v1, s[6:7]
	s_add_u32 s6, s8, 64
	s_addc_u32 s7, s9, 0
	s_add_i32 s8, s58, 0x6000
	s_mov_b32 m0, s8
	s_nop 0
	global_load_lds_dwordx4 v1, s[6:7]
	s_add_u32 s6, s16, 64
	s_addc_u32 s7, s17, 0
	s_add_i32 s8, s57, 0x6000
	s_mov_b32 m0, s8
	s_nop 0
	global_load_lds_dwordx4 v1, s[6:7]
	s_add_u32 s6, s14, 64
	s_addc_u32 s7, s15, 0
	s_add_i32 s8, s56, 0x6000
	s_mov_b32 m0, s8
	s_nop 0
	global_load_lds_dwordx4 v1, s[6:7]
	s_add_u32 s6, s12, 64
	s_addc_u32 s7, s13, 0
	s_add_i32 s55, s55, 0xa000
	s_mov_b32 m0, s55
	s_nop 0
	global_load_lds_dwordx4 v1, s[6:7]
	s_add_u32 s6, s10, 64
	s_addc_u32 s7, s11, 0
	s_add_i32 s54, s54, 0xa000
	s_mov_b32 m0, s54
	s_nop 0
	global_load_lds_dwordx4 v1, s[6:7]
	s_branch .LBB0_145

; DEV int otid() { int t = threadIdx.x; asm volatile("" : "+v"(t)); return t; }
;   const int tid = otid(), lane = tid & 63, w = __builtin_amdgcn_readfirstlane(tid >> 6), wm = w >> 1, wn = w & 1, r32 = lane & 31, hh = lane >> 5;
;   f32x16 acc[MI / 2][2][2];
; #pragma unroll
;   for (int h = 0; h < MI / 2; ++h) { acc[h][0][0] = zero16(); acc[h][0][1] = zero16(); acc[h][1][0] = zero16(); acc[h][1][1] = zero16(); }
;   const int lrow = lane >> 2, lp = (lane & 3) ^ ((lane >> 4) & 3);
;   const bf16_t* ag = uni_ptr(A + (size_t)m0 * lda + kbeg);
;   const bf16_t* bg = uni_ptr(Bt + (size_t)n0 * ldb + kbeg);
;   const unsigned voffa = ((unsigned)lrow * (unsigned)lda + (unsigned)lp * 8u) * 2u;
;   const unsigned voffb = ((unsigned)lrow * (unsigned)ldb + (unsigned)lp * 8u) * 2u;
;   const int nk = (kend - kbeg) >> 5;
;   if (!pre) {
;     asm volatile("s_waitcnt vmcnt(0)" ::: "memory");
;     g2_issue<MI>(ag, bg, lda, ldb, voffa, voffb, lds, w);
;     if (nk > 1) g2_issue<MI>(ag + 32, bg + 32, lda, ldb, voffa, voffb, lds + G2_STAGE, w);
;   }
;   const int key = (r32 >> 2) & 3;
;   const int aoff = (wm * (MI * 32) + r32) * 64;
;   const int boff = 16384 + (wn * 64 + r32) * 64;
;   const int p0 = ((0 + hh) ^ key) * 16, p1 = ((2 + hh) ^ key) * 16;
;   const unsigned lbase = (unsigned)(size_t)lds;
;   const unsigned la0 = lbase + aoff + p0, la1 = lbase + aoff + p1, lb0 = lbase + boff + p0, lb1 = lbase + boff + p1;
;   int stg = 0;
;   for (int kt = 0; kt < nk; ++kt) {
;     if (kt + 1 < nk) { if (MI == 4) asm volatile("s_waitcnt vmcnt(6)" ::: "memory"); else asm volatile("s_waitcnt vmcnt(4)" ::: "memory"); } else asm volatile("s_waitcnt vmcnt(0)" ::: "memory");
;     __builtin_amdgcn_s_barrier();
;     if (kt + 2 < nk) { int s2 = stg + 2; if (s2 >= 3) s2 -= 3; g2_issue<MI>(ag + (size_t)(kt + 2) * 32, bg + (size_t)(kt + 2) * 32, lda, ldb, voffa, voffb, lds + s2 * G2_STAGE, w); }
.LBB0_536:
	s_xor_b64 s[12:13], s[2:3], -1
	v_writelane_b32 v239, s12, 34
	s_and_b32 s62, s14, 0xffffff80
	s_and_b32 s61, s14, 64
	v_writelane_b32 v239, s13, 35
	s_lshl_b64 s[16:17], s[4:5], 12
	s_lshl_b64 s[14:15], s[6:7], 12
	s_lshl_b64 s[12:13], s[8:9], 12
	s_lshl_b64 s[10:11], s[10:11], 12
	s_lshl_b64 s[8:9], s[18:19], 12
	s_lshl_b64 s[4:5], s[20:21], 12
	s_add_u32 s18, s59, 0x80
	s_addc_u32 s19, s63, 0
	s_add_u32 s6, s18, s4
	s_addc_u32 s7, s19, s5
	s_add_u32 s20, s18, s8
	s_addc_u32 s21, s19, s9
	s_add_u32 s18, s57, 0x80
	s_addc_u32 s19, s58, 0
	s_add_u32 s57, s18, s10
	s_addc_u32 s58, s19, s11
	v_and_b32_e32 v2, 63, v130
	s_add_u32 s59, s18, s12
	v_lshrrev_b32_e32 v133, 5, v2
	v_lshrrev_b32_e32 v2, 2, v130
	s_addc_u32 s63, s19, s13
	v_and_b32_e32 v152, 31, v130
	v_bfe_u32 v3, v130, 2, 2
	v_bitop3_b32 v2, v133, v2, 3 bitop3:0x78
	s_add_u32 s74, s18, s14
	v_or_b32_e32 v143, s61, v152
	v_lshlrev_b32_e32 v147, 4, v2
	v_bitop3_b32 v2, v133, v3, 2 bitop3:0x36
	s_addc_u32 s75, s19, s15
	v_or_b32_e32 v4, s62, v152
	v_lshlrev_b32_e32 v149, 6, v143
	v_lshlrev_b32_e32 v145, 4, v2
	s_add_u32 s76, s18, s16
	v_mov_b32_e32 v2, 0
	v_lshlrev_b32_e32 v138, 6, v4
	v_or_b32_e32 v141, 0x4000, v149
	s_addc_u32 s77, s19, s17
	s_mov_b32 s79, 0
	s_mov_b64 s[18:19], 0
	v_mov_b32_e32 v3, v2
	v_mov_b32_e32 v4, v2
	v_mov_b32_e32 v5, v2
	v_mov_b32_e32 v6, v2
	v_mov_b32_e32 v7, v2
	v_mov_b32_e32 v8, v2
	v_mov_b32_e32 v9, v2
	v_mov_b32_e32 v10, v2
	v_mov_b32_e32 v11, v2
	v_mov_b32_e32 v12, v2
	v_mov_b32_e32 v13, v2
	v_mov_b32_e32 v14, v2
	v_mov_b32_e32 v15, v2
	v_mov_b32_e32 v16, v2
	v_mov_b32_e32 v17, v2
	v_mov_b32_e32 v18, v2
	v_mov_b32_e32 v19, v2
	v_mov_b32_e32 v20, v2
	v_mov_b32_e32 v21, v2
	v_mov_b32_e32 v22, v2
	v_mov_b32_e32 v23, v2
	v_mov_b32_e32 v24, v2
	v_mov_b32_e32 v25, v2
	v_mov_b32_e32 v26, v2
	v_mov_b32_e32 v27, v2
	v_mov_b32_e32 v28, v2
	v_mov_b32_e32 v29, v2
	v_mov_b32_e32 v30, v2
	v_mov_b32_e32 v31, v2
	v_mov_b32_e32 v32, v2
	v_mov_b32_e32 v33, v2
	v_mov_b32_e32 v34, v2
	v_mov_b32_e32 v35, v2
	v_mov_b32_e32 v36, v2
	v_mov_b32_e32 v37, v2
	v_mov_b32_e32 v38, v2
	v_mov_b32_e32 v39, v2
	v_mov_b32_e32 v40, v2
	v_mov_b32_e32 v41, v2
	v_mov_b32_e32 v42, v2
	v_mov_b32_e32 v43, v2
	v_mov_b32_e32 v44, v2
	v_mov_b32_e32 v45, v2
	v_mov_b32_e32 v46, v2
	v_mov_b32_e32 v47, v2
	v_mov_b32_e32 v48, v2
	v_mov_b32_e32 v49, v2
	v_mov_b32_e32 v50, v2
	v_mov_b32_e32 v51, v2
	v_mov_b32_e32 v52, v2
	v_mov_b32_e32 v53, v2
	v_mov_b32_e32 v54, v2
	v_mov_b32_e32 v55, v2
	v_mov_b32_e32 v56, v2
	v_mov_b32_e32 v57, v2
	v_mov_b32_e32 v58, v2
	v_mov_b32_e32 v59, v2
	v_mov_b32_e32 v60, v2
	v_mov_b32_e32 v61, v2
	v_mov_b32_e32 v62, v2
	v_mov_b32_e32 v63, v2
	v_mov_b32_e32 v64, v2
	v_mov_b32_e32 v65, v2
	v_mov_b32_e32 v66, v2
	v_mov_b32_e32 v67, v2
	v_mov_b32_e32 v68, v2
	v_mov_b32_e32 v69, v2
	v_mov_b32_e32 v70, v2
	v_mov_b32_e32 v71, v2
	v_mov_b32_e32 v72, v2
	v_mov_b32_e32 v73, v2
	v_mov_b32_e32 v74, v2
	v_mov_b32_e32 v75, v2
	v_mov_b32_e32 v76, v2
	v_mov_b32_e32 v77, v2
	v_mov_b32_e32 v78, v2
	v_mov_b32_e32 v79, v2
	v_mov_b32_e32 v80, v2
	v_mov_b32_e32 v81, v2
	v_mov_b32_e32 v82, v2
	v_mov_b32_e32 v83, v2
	v_mov_b32_e32 v84, v2
	v_mov_b32_e32 v85, v2
	v_mov_b32_e32 v86, v2
	v_mov_b32_e32 v87, v2
	v_mov_b32_e32 v88, v2
	v_mov_b32_e32 v89, v2
	v_mov_b32_e32 v90, v2
	v_mov_b32_e32 v91, v2
	v_mov_b32_e32 v92, v2
	v_mov_b32_e32 v93, v2
	v_mov_b32_e32 v94, v2
	v_mov_b32_e32 v95, v2
	v_mov_b32_e32 v96, v2
	v_mov_b32_e32 v97, v2
	v_mov_b32_e32 v98, v2
	v_mov_b32_e32 v99, v2
	v_mov_b32_e32 v100, v2
	v_mov_b32_e32 v101, v2
	v_mov_b32_e32 v102, v2
	v_mov_b32_e32 v103, v2
	v_mov_b32_e32 v104, v2
	v_mov_b32_e32 v105, v2
	v_mov_b32_e32 v106, v2
	v_mov_b32_e32 v107, v2
	v_mov_b32_e32 v108, v2
	v_mov_b32_e32 v109, v2
	v_mov_b32_e32 v110, v2
	v_mov_b32_e32 v111, v2
	v_mov_b32_e32 v112, v2
	v_mov_b32_e32 v113, v2
	v_mov_b32_e32 v114, v2
	v_mov_b32_e32 v115, v2
	v_mov_b32_e32 v116, v2
	v_mov_b32_e32 v117, v2
	v_mov_b32_e32 v118, v2
	v_mov_b32_e32 v119, v2
	v_mov_b32_e32 v120, v2
	v_mov_b32_e32 v121, v2
	v_mov_b32_e32 v122, v2
	v_mov_b32_e32 v123, v2
	v_mov_b32_e32 v124, v2
	v_mov_b32_e32 v125, v2
	v_mov_b32_e32 v126, v2
	v_mov_b32_e32 v127, v2
	v_mov_b32_e32 v128, v2
	v_mov_b32_e32 v129, v2
	v_lshlrev_b32_e32 v254, 4, v200
.LBB0_537:
	s_cmp_gt_i32 s79, 0
	s_cselect_b32 s80, -1, 2
	s_add_i32 s80, s80, s79
	s_mul_i32 s82, s80, 0x6000
	s_add_u32 s80, s76, s18
	s_addc_u32 s81, s77, s19
	s_add_i32 s83, s1, s82
	s_cmp_eq_u32 s18, 0
	s_cbranch_scc1 .Lhy4_first_out
	s_waitcnt vmcnt(0)
	s_barrier
	s_add_i32 s98, s79, 1
	s_cmp_lg_u32 s79, 2
	s_cselect_b32 s98, s98, 0
	s_mul_i32 s98, s98, 0x6000
	s_add_i32 s99, s1, s98
	v_add_u32_e32 v238, s99, v254
	ds_write_b128 v238, v[214:217]
	s_add_i32 s99, s26, s98
	v_add_u32_e32 v255, s99, v254
	ds_write_b128 v255, v[218:221]
	s_add_i32 s99, s27, s98
	v_add_u32_e32 v238, s99, v254
	ds_write_b128 v238, v[222:225]
	s_add_i32 s99, s28, s98
	v_add_u32_e32 v255, s99, v254
	ds_write_b128 v255, v[226:229]
	s_add_i32 s99, s30, s98
	s_addk_i32 s99, 0x4000
	v_add_u32_e32 v238, s99, v254
	ds_write_b128 v238, v[230:233]
	s_add_i32 s99, s31, s98
	s_addk_i32 s99, 0x4000
	v_add_u32_e32 v255, s99, v254
	ds_write_b128 v255, v[234:237]
	s_branch .Lhy4_issue_out

; DEV f32x16 mfma(bf16x8 a, bf16x8 b, f32x16 c) { return __builtin_amdgcn_mfma_f32_32x32x16_bf16(a, b, c, 0, 0, 0); }
;     ...
;     if (kt + 1 < nk) { if (MI == 4) asm volatile("s_waitcnt vmcnt(6)" ::: "memory"); else asm volatile("s_waitcnt vmcnt(4)" ::: "memory"); } else asm volatile("s_waitcnt vmcnt(0)" ::: "memory");
;     __builtin_amdgcn_s_barrier();
;     if (kt + 2 < nk) { int s2 = stg + 2; if (s2 >= 3) s2 -= 3; g2_issue<MI>(ag + (size_t)(kt + 2) * 32, bg + (size_t)(kt + 2) * 32, lda, ldb, voffa, voffb, lds + s2 * G2_STAGE, w); }
;     const unsigned so = (unsigned)(stg * G2_STAGE);
;     __builtin_amdgcn_s_setprio(1);
; #pragma unroll
;     for (int ks = 0; ks < 2; ++ks) {
;       const unsigned aa = (ks ? la1 : la0) + so, bb = (ks ? lb1 : lb0) + so;
;       bf16x8 fb0, fb1, fa0, fa1, fa2, fa3;
;       asm volatile("ds_read_b128 %0, %1" : "=v"(fb0) : "v"(bb));
;       asm volatile("ds_read_b128 %0, %1 offset:2048" : "=v"(fb1) : "v"(bb));
;       asm volatile("ds_read_b128 %0, %1" : "=v"(fa0) : "v"(aa));
;       asm volatile("ds_read_b128 %0, %1 offset:2048" : "=v"(fa1) : "v"(aa));
;       if constexpr (MI == 4) {
;         asm volatile("ds_read_b128 %0, %1 offset:4096" : "=v"(fa2) : "v"(aa));
;         asm volatile("ds_read_b128 %0, %1 offset:6144" : "=v"(fa3) : "v"(aa));
;         __builtin_amdgcn_sched_barrier(0);
;         asm volatile("s_waitcnt lgkmcnt(3)" : "+v"(fb0), "+v"(fb1), "+v"(fa0));
;         acc[0][0][0] = mfma(fa0, fb0, acc[0][0][0]); acc[0][0][1] = mfma(fa0, fb1, acc[0][0][1]); __builtin_amdgcn_sched_barrier(0);
;         asm volatile("s_waitcnt lgkmcnt(2)" : "+v"(fa1));
;         acc[0][1][0] = mfma(fa1, fb0, acc[0][1][0]); acc[0][1][1] = mfma(fa1, fb1, acc[0][1][1]); __builtin_amdgcn_sched_barrier(0);
;         asm volatile("s_waitcnt lgkmcnt(1)" : "+v"(fa2));
;         acc[MI / 2 - 1][0][0] = mfma(fa2, fb0, acc[MI / 2 - 1][0][0]); acc[MI / 2 - 1][0][1] = mfma(fa2, fb1, acc[MI / 2 - 1][0][1]); __builtin_amdgcn_sched_barrier(0);
;         asm volatile("s_waitcnt lgkmcnt(0)" : "+v"(fa3));
;         acc[MI / 2 - 1][1][0] = mfma(fa3, fb0, acc[MI / 2 - 1][1][0]); acc[MI / 2 - 1][1][1] = mfma(fa3, fb1, acc[MI / 2 - 1][1][1]); __builtin_amdgcn_sched_barrier(0);
.Lhy4_issue_out:
	s_mul_i32 s99, s79, 0x6000
	s_setprio 1
	v_add_u32_e32 v153, s99, v138
	v_add_u32_e32 v178, s99, v141
	v_add_u32_e32 v174, v153, v147
	v_add_u32_e32 v158, v178, v147
	ds_read_b128 v[154:157], v158
	ds_read_b128 v[158:161], v158 offset:2048
	ds_read_b128 v[162:165], v174
	ds_read_b128 v[166:169], v174 offset:2048
	ds_read_b128 v[170:173], v174 offset:4096
	ds_read_b128 v[174:177], v174 offset:6144
	v_add_u32_e32 v238, v178, v145
	v_add_u32_e32 v153, v153, v145
	ds_read_b128 v[180:183], v238
	ds_read_b128 v[184:187], v238 offset:2048
	ds_read_b128 v[188:191], v153
	ds_read_b128 v[242:245], v153 offset:2048
	ds_read_b128 v[246:249], v153 offset:4096
	ds_read_b128 v[250:253], v153 offset:6144
	s_cmpk_eq_i32 s18, 0xf80
	s_cbranch_scc1 .Lhy4_noissueE_out
	s_nop 0
	s_waitcnt lgkmcnt(9)
	s_nop 0
	v_mfma_f32_32x32x16_bf16 v[114:129], v[162:165], v[154:157], v[114:129]
	v_mfma_f32_32x32x16_bf16 v[98:113], v[162:165], v[158:161], v[98:113]
	s_mov_b32 m0, s83
	s_nop 0
	global_load_lds_dwordx4 v1, s[80:81]
	global_load_dwordx4 v[214:217], v1, s[80:81] offset:64
	s_waitcnt lgkmcnt(8)
	s_nop 0
	v_mfma_f32_32x32x16_bf16 v[82:97], v[166:169], v[154:157], v[82:97]
	v_mfma_f32_32x32x16_bf16 v[66:81], v[166:169], v[158:161], v[66:81]
	s_add_u32 s80, s74, s18
	s_addc_u32 s81, s75, s19
	s_add_i32 s83, s26, s82
	s_mov_b32 m0, s83
	s_nop 0
	global_load_lds_dwordx4 v1, s[80:81]
	global_load_dwordx4 v[218:221], v1, s[80:81] offset:64
	s_waitcnt lgkmcnt(7)
	s_nop 0
	v_mfma_f32_32x32x16_bf16 v[50:65], v[170:173], v[154:157], v[50:65]
	v_mfma_f32_32x32x16_bf16 v[34:49], v[170:173], v[158:161], v[34:49]
	s_add_u32 s80, s59, s18
	s_addc_u32 s81, s63, s19
	s_add_i32 s83, s27, s82
	s_mov_b32 m0, s83
	s_nop 0
	global_load_lds_dwordx4 v1, s[80:81]
	global_load_dwordx4 v[222:225], v1, s[80:81] offset:64
	s_waitcnt lgkmcnt(6)
	s_nop 0
	v_mfma_f32_32x32x16_bf16 v[18:33], v[174:177], v[154:157], v[18:33]
	v_mfma_f32_32x32x16_bf16 v[2:17], v[174:177], v[158:161], v[2:17]
	s_branch .Lhy4_afterE_out
.Lhy4_noissueE_out:
	s_nop 0
	s_waitcnt lgkmcnt(9)
	s_nop 0
	v_mfma_f32_32x32x16_bf16 v[114:129], v[162:165], v[154:157], v[114:129]
	v_mfma_f32_32x32x16_bf16 v[98:113], v[162:165], v[158:161], v[98:113]
	s_waitcnt lgkmcnt(8)
	s_nop 0
	v_mfma_f32_32x32x16_bf16 v[82:97], v[166:169], v[154:157], v[82:97]
	v_mfma_f32_32x32x16_bf16 v[66:81], v[166:169], v[158:161], v[66:81]
	s_waitcnt lgkmcnt(7)
	s_nop 0
	v_mfma_f32_32x32x16_bf16 v[50:65], v[170:173], v[154:157], v[50:65]
	v_mfma_f32_32x32x16_bf16 v[34:49], v[170:173], v[158:161], v[34:49]
	s_waitcnt lgkmcnt(6)
	s_nop 0
	v_mfma_f32_32x32x16_bf16 v[18:33], v[174:177], v[154:157], v[18:33]
	v_mfma_f32_32x32x16_bf16 v[2:17], v[174:177], v[158:161], v[2:17]
.Lhy4_afterE_out:
	s_nop 0
	s_waitcnt lgkmcnt(3)
	s_nop 0
	v_mfma_f32_32x32x16_bf16 v[114:129], v[188:191], v[180:183], v[114:129]
	v_mfma_f32_32x32x16_bf16 v[98:113], v[188:191], v[184:187], v[98:113]
	s_waitcnt lgkmcnt(2)
	s_nop 0
	v_mfma_f32_32x32x16_bf16 v[82:97], v[242:245], v[180:183], v[82:97]
	v_mfma_f32_32x32x16_bf16 v[66:81], v[242:245], v[184:187], v[66:81]
	s_waitcnt lgkmcnt(1)
	s_nop 0
	v_mfma_f32_32x32x16_bf16 v[50:65], v[246:249], v[180:183], v[50:65]
	v_mfma_f32_32x32x16_bf16 v[34:49], v[246:249], v[184:187], v[34:49]
	s_waitcnt lgkmcnt(0)
	s_nop 0
	v_mfma_f32_32x32x16_bf16 v[18:33], v[250:253], v[180:183], v[18:33]
	v_mfma_f32_32x32x16_bf16 v[2:17], v[250:253], v[184:187], v[2:17]
	s_setprio 0
	s_add_i32 s98, s79, 1
	s_cmp_lg_u32 s79, 2
	s_cselect_b32 s79, s98, 0
	s_waitcnt vmcnt(6)
	s_barrier
	s_mul_i32 s99, s79, 0x6000
	s_setprio 1
	v_add_u32_e32 v153, s99, v138
	v_add_u32_e32 v178, s99, v141
	v_add_u32_e32 v174, v153, v147
	v_add_u32_e32 v158, v178, v147
	ds_read_b128 v[154:157], v158
	ds_read_b128 v[158:161], v158 offset:2048
	ds_read_b128 v[162:165], v174
	ds_read_b128 v[166:169], v174 offset:2048
	ds_read_b128 v[170:173], v174 offset:4096
	ds_read_b128 v[174:177], v174 offset:6144
	v_add_u32_e32 v238, v178, v145
	v_add_u32_e32 v153, v153, v145
	ds_read_b128 v[180:183], v238
	ds_read_b128 v[184:187], v238 offset:2048
	ds_read_b128 v[188:191], v153
	ds_read_b128 v[242:245], v153 offset:2048
	ds_read_b128 v[246:249], v153 offset:4096
	ds_read_b128 v[250:253], v153 offset:6144
	s_cmpk_eq_i32 s18, 0xf80
	s_cbranch_scc1 .Lhy4_noissueO_out
	s_nop 0
	s_waitcnt lgkmcnt(9)
	s_nop 0
	v_mfma_f32_32x32x16_bf16 v[114:129], v[162:165], v[154:157], v[114:129]
	v_mfma_f32_32x32x16_bf16 v[98:113], v[162:165], v[158:161], v[98:113]
	s_add_u32 s80, s57, s18
	s_addc_u32 s81, s58, s19
	s_add_i32 s83, s28, s82
	s_addk_i32 s82, 0x4000
	s_mov_b32 m0, s83
	s_nop 0
	global_load_lds_dwordx4 v1, s[80:81]
	global_load_dwordx4 v[226:229], v1, s[80:81] offset:64
	s_waitcnt lgkmcnt(8)
	s_nop 0
	v_mfma_f32_32x32x16_bf16 v[82:97], v[166:169], v[154:157], v[82:97]
	v_mfma_f32_32x32x16_bf16 v[66:81], v[166:169], v[158:161], v[66:81]
	s_add_u32 s80, s20, s18
	s_addc_u32 s81, s21, s19
	s_add_i32 s83, s82, s30
	s_mov_b32 m0, s83
	s_nop 0
	global_load_lds_dwordx4 v1, s[80:81]
	global_load_dwordx4 v[230:233], v1, s[80:81] offset:64
	s_waitcnt lgkmcnt(7)
	s_nop 0
	v_mfma_f32_32x32x16_bf16 v[50:65], v[170:173], v[154:157], v[50:65]
	v_mfma_f32_32x32x16_bf16 v[34:49], v[170:173], v[158:161], v[34:49]
	s_add_u32 s80, s6, s18
	s_addc_u32 s81, s7, s19
	s_add_i32 s82, s82, s31
	s_mov_b32 m0, s82
	s_nop 0
	global_load_lds_dwordx4 v1, s[80:81]
	global_load_dwordx4 v[234:237], v1, s[80:81] offset:64
	s_waitcnt lgkmcnt(6)
	s_nop 0
	v_mfma_f32_32x32x16_bf16 v[18:33], v[174:177], v[154:157], v[18:33]
	v_mfma_f32_32x32x16_bf16 v[2:17], v[174:177], v[158:161], v[2:17]
	s_branch .Lhy4_afterO_out

; DEV f32x16 mfma(bf16x8 a, bf16x8 b, f32x16 c) { return __builtin_amdgcn_mfma_f32_32x32x16_bf16(a, b, c, 0, 0, 0); }
;     ...
;         acc[0][1][0] = mfma(fa1, fb0, acc[0][1][0]); acc[0][1][1] = mfma(fa1, fb1, acc[0][1][1]); __builtin_amdgcn_sched_barrier(0);
;         asm volatile("s_waitcnt lgkmcnt(1)" : "+v"(fa2));
;         acc[MI / 2 - 1][0][0] = mfma(fa2, fb0, acc[MI / 2 - 1][0][0]); acc[MI / 2 - 1][0][1] = mfma(fa2, fb1, acc[MI / 2 - 1][0][1]); __builtin_amdgcn_sched_barrier(0);
;         asm volatile("s_waitcnt lgkmcnt(0)" : "+v"(fa3));
;         acc[MI / 2 - 1][1][0] = mfma(fa3, fb0, acc[MI / 2 - 1][1][0]); acc[MI / 2 - 1][1][1] = mfma(fa3, fb1, acc[MI / 2 - 1][1][1]); __builtin_amdgcn_sched_barrier(0);
;       } else {
;         __builtin_amdgcn_sched_barrier(0);
;         asm volatile("s_waitcnt lgkmcnt(1)" : "+v"(fb0), "+v"(fb1), "+v"(fa0));
;         acc[0][0][0] = mfma(fa0, fb0, acc[0][0][0]); acc[0][0][1] = mfma(fa0, fb1, acc[0][0][1]); __builtin_amdgcn_sched_barrier(0);
;         asm volatile("s_waitcnt lgkmcnt(0)" : "+v"(fa1));
;         acc[0][1][0] = mfma(fa1, fb0, acc[0][1][0]); acc[0][1][1] = mfma(fa1, fb1, acc[0][1][1]); __builtin_amdgcn_sched_barrier(0);
;       }
;     }
;     __builtin_amdgcn_s_setprio(0);
;     stg = stg == 2 ? 0 : stg + 1;
;   }
;   __syncthreads();
;   if (has_next) {
;     const bf16_t* agn = uni_ptr(A + (size_t)m0n * lda + kbeg);
;     const bf16_t* bgn = uni_ptr(Bt + (size_t)n0n * ldb + kbeg);
;     g2_issue<MI>(agn, bgn, lda, ldb, voffa, voffb, lds, w);
;     g2_issue<MI>(agn + 32, bgn + 32, lda, ldb, voffa, voffb, lds + G2_STAGE, w);
.Lhy4_afterO_out:
	s_nop 0
	s_waitcnt lgkmcnt(3)
	s_nop 0
	v_mfma_f32_32x32x16_bf16 v[114:129], v[188:191], v[180:183], v[114:129]
	v_mfma_f32_32x32x16_bf16 v[98:113], v[188:191], v[184:187], v[98:113]
	s_waitcnt lgkmcnt(2)
	s_nop 0
	v_mfma_f32_32x32x16_bf16 v[82:97], v[242:245], v[180:183], v[82:97]
	v_mfma_f32_32x32x16_bf16 v[66:81], v[242:245], v[184:187], v[66:81]
	s_waitcnt lgkmcnt(1)
	s_nop 0
	v_mfma_f32_32x32x16_bf16 v[50:65], v[246:249], v[180:183], v[50:65]
	v_mfma_f32_32x32x16_bf16 v[34:49], v[246:249], v[184:187], v[34:49]
	s_waitcnt lgkmcnt(0)
	s_nop 0
	v_mfma_f32_32x32x16_bf16 v[18:33], v[250:253], v[180:183], v[18:33]
	v_mfma_f32_32x32x16_bf16 v[2:17], v[250:253], v[184:187], v[2:17]
	s_add_i32 s98, s79, 1
	s_cmp_lg_u32 s79, 2
	s_cselect_b32 s79, s98, 0
	s_add_u32 s18, s18, 0x80
	s_addc_u32 s19, s19, 0
	s_cmpk_eq_i32 s18, 0x1000
	s_cbranch_scc0 .LBB0_537
	s_setprio 0
	s_and_b64 vcc, exec, s[2:3]
	s_waitcnt lgkmcnt(0)
	s_barrier
	s_cbranch_vccz .LBB0_540
	s_lshl_b32 s2, s53, 8
	s_ashr_i32 s3, s2, 31
	s_lshl_b32 s6, s54, 7
	s_lshl_b64 s[2:3], s[2:3], 12
	s_add_u32 s18, s24, s2
	s_addc_u32 s19, s25, s3
	s_ashr_i32 s7, s6, 31
	s_lshl_b64 s[2:3], s[6:7], 12
	s_add_u32 s20, s22, s2
	s_addc_u32 s21, s23, s3
	s_add_u32 s2, s18, s16
	s_addc_u32 s3, s19, s17
	s_add_u32 s6, s18, s14
	s_addc_u32 s7, s19, s15
	s_add_u32 s12, s18, s12
	s_addc_u32 s13, s19, s13
	s_add_u32 s10, s18, s10
	s_mov_b32 m0, s1
	s_nop 0
	global_load_lds_dwordx4 v1, s[2:3]
	s_addc_u32 s11, s19, s11
	s_mov_b32 m0, s26
	s_nop 0
	global_load_lds_dwordx4 v1, s[6:7]
	s_add_u32 s8, s20, s8
	s_mov_b32 m0, s27
	s_nop 0
	global_load_lds_dwordx4 v1, s[12:13]
	s_addc_u32 s9, s21, s9
	s_add_i32 s14, s30, 0x4000
	s_mov_b32 m0, s28
	s_nop 0
	global_load_lds_dwordx4 v1, s[10:11]
	s_add_u32 s4, s20, s4
	s_mov_b32 m0, s14
	s_nop 0
	global_load_lds_dwordx4 v1, s[8:9]
	s_addc_u32 s5, s21, s5
	s_add_i32 s14, s31, 0x4000
	s_add_u32 s2, s2, 64
	s_mov_b32 m0, s14
	s_nop 0
	global_load_lds_dwordx4 v1, s[4:5]
	s_addc_u32 s3, s3, 0
	s_addk_i32 s1, 0x6000
	s_mov_b32 m0, s1
	s_nop 0
	global_load_lds_dwordx4 v1, s[2:3]
	s_add_u32 s2, s6, 64
	s_addc_u32 s3, s7, 0
	s_add_i32 s1, s26, 0x6000
	s_mov_b32 m0, s1
	s_nop 0
	global_load_lds_dwordx4 v1, s[2:3]
	s_add_u32 s2, s12, 64
	s_addc_u32 s3, s13, 0
	s_add_i32 s1, s27, 0x6000
	s_mov_b32 m0, s1
	s_nop 0
	global_load_lds_dwordx4 v1, s[2:3]
	s_add_u32 s2, s10, 64
	s_addc_u32 s3, s11, 0
	s_add_i32 s1, s28, 0x6000
	s_mov_b32 m0, s1
	s_nop 0
	global_load_lds_dwordx4 v1, s[2:3]
	s_add_u32 s2, s8, 64
	s_addc_u32 s3, s9, 0
	s_add_i32 s1, s30, 0xa000
	s_mov_b32 m0, s1
	s_nop 0
	global_load_lds_dwordx4 v1, s[2:3]
	s_add_u32 s2, s4, 64
	s_addc_u32 s3, s5, 0
	s_add_i32 s1, s31, 0xa000
	s_mov_b32 m0, s1
	s_nop 0
	global_load_lds_dwordx4 v1, s[2:3]
